# hand-written rw_post: four rows' reduction and correction chains interleaved
# baseline (speedup 1.0000x reference)
; #define POST_LD(Y_, V_, G_, R_, C_, t) do { _Pragma("unroll") for (int q = 0; q < 8; ++q) { const size_t o_ = (size_t)((t) + q) * DH; Y_[q] = yp[o_]; V_[q] = vp[o_]; G_[q] = gp[o_]; R_[q] = rp[((t) + q) * 32]; C_[q] = cp[o_]; } } while (0)
; __device__ __forceinline__ void rw_post(Frame& F) {
;     const float* Y = (const float*)(F.ws + WS_Y); const float* C = (const float*)(F.ws + WS_C); const float* SST = (const float*)(F.ws + WS_SST); const float* VS = (const float*)(F.ws + WS_VS);
;     const float* RK = (const float*)(F.ws + WS_RK); const bf16* G = (const bf16*)(F.ws + WS_G);
;     bf16* OB = (bf16*)(F.ws + WS_OB); const float* lng = F.in[I_LNG]; const float* lnb = F.in[I_LNB];
;     const int lane = F.lane;
;     for (int u = F.gw; u < 32 * (MR / 64); u += F.NGW) { const int h = u & 31, rb0 = (u >> 5) * 64, col = h * 64 + lane;
;         const float g_ = lng[col], b_ = lnb[col];
;         const int k = rb0 < MPR ? (rb0 / SEGLEN) : 0;
;         f32x4 Sr[16];
;         if (k > 0) {
; #pragma unroll
;             for (int q = 0; q < 16; ++q) Sr[q] = *(const f32x4*)(SST + ((size_t)(h * NSEG + k) * 64 + lane) * 64 + 4 * q); }
;         const float* yp = Y + (size_t)rb0 * DH + col; const float* vp = VS + (size_t)rb0 * DH + col; const bf16* gp = G + (size_t)rb0 * DH + col; const float* rp = RK + (size_t)rb0 * 32 + h;
;         const float* cp = k > 0 ? C + (size_t)(rb0 - SEGLEN) * DH + col : yp;
;         float y[8], vv[8], rk[8], cc[8]; bf16 gg[8];
;     ...
;         POST_LD(y, vv, gg, rk, cc, 0);
.LBB0_1160:
	s_or_b64 exec, exec, s[6:7]
	s_cmpk_gt_i32 s94, 0x203f
	s_waitcnt lgkmcnt(0)
	s_barrier
	s_cbranch_scc1 .LBB0_1170
	s_load_dwordx4 s[16:19], s[74:75], 0xc0
	v_readlane_b32 s24, v240, 2
	v_lshlrev_b32_e32 v1, 2, v178
	v_lshlrev_b32_e32 v2, 1, v178
	v_lshlrev_b32_e32 v10, 8, v178
	v_mov_b32_e32 v5, 0
	v_mov_b32_e32 v8, 0x260
	v_mov_b32_e32 v9, 0x3a27c5ac
	s_mov_b32 s68, 0xf800000
	s_lshl_b32 s24, s24, 10
	s_add_i32 s24, s24, 0x20000
	v_mov_b32_e32 v4, s24
	v_add_u32_e32 v3, s24, v1
	s_mov_b32 s20, s94
	s_waitcnt lgkmcnt(0)
.Lpo_unit:
	s_and_b32 s21, s20, 31
	s_lshr_b32 s22, s20, 5
	s_lshl_b32 s22, s22, 6
	s_lshr_b32 s23, s22, 10
	s_cmpk_lt_i32 s22, 0x4000
	s_cselect_b32 s23, s23, 0
	s_lshl_b32 s30, s22, 13
	s_lshl_b32 s31, s21, 8
	s_add_u32 s30, s30, s31
	s_add_u32 s6, s90, s30
	s_addc_u32 s7, s91, 0
	s_add_u32 s8, s6, 0x28700000
	s_addc_u32 s9, s7, 0
	s_add_u32 s14, s6, 0x39900000
	s_addc_u32 s15, s7, 0
	s_add_u32 s34, s6, 0x41200000
	s_addc_u32 s35, s7, 0
	s_add_u32 s6, s6, 0x39900000
	s_addc_u32 s7, s7, 0
	s_cmp_eq_u32 s23, 0
	s_cselect_b32 s14, s14, s34
	s_cselect_b32 s15, s15, s35
	s_lshl_b32 s30, s22, 12
	s_lshl_b32 s31, s21, 7
	s_add_u32 s30, s30, s31
	s_add_u32 s10, s90, s30
	s_addc_u32 s11, s91, 0
	s_add_u32 s28, s10, 0x18500000
	s_addc_u32 s29, s11, 0
	s_add_u32 s10, s10, 0x30800000
	s_addc_u32 s11, s11, 0
	s_lshl_b32 s30, s22, 7
	s_lshl_b32 s31, s21, 2
	s_add_u32 s30, s30, s31
	s_add_u32 s12, s90, s30
	s_addc_u32 s13, s91, 0
	s_add_u32 s12, s12, 0x6e200000
	s_addc_u32 s13, s13, 0
	s_lshl_b32 s31, s21, 8
	s_add_u32 s30, s16, s31
	s_addc_u32 s31, s17, 0
	global_load_dword v6, v1, s[30:31]
	s_lshl_b32 s31, s21, 8
	s_add_u32 s30, s18, s31
	s_addc_u32 s31, s19, 0
	global_load_dword v7, v1, s[30:31]
	s_cmp_eq_u32 s23, 0
	s_cbranch_scc1 .Lpo_nosr
	s_lshl_b32 s30, s21, 4
	s_add_u32 s30, s30, s23
	s_lshl_b32 s30, s30, 14
	s_add_u32 s30, s90, s30
	s_addc_u32 s31, s91, 0
	s_add_u32 s30, s30, 0x6fb00000
	s_addc_u32 s31, s31, 0
	global_load_dwordx4 v[16:19], v10, s[30:31]
	global_load_dwordx4 v[20:23], v10, s[30:31] offset:16
	global_load_dwordx4 v[24:27], v10, s[30:31] offset:32
	global_load_dwordx4 v[28:31], v10, s[30:31] offset:48
	global_load_dwordx4 v[32:35], v10, s[30:31] offset:64
	global_load_dwordx4 v[36:39], v10, s[30:31] offset:80
	global_load_dwordx4 v[40:43], v10, s[30:31] offset:96
	global_load_dwordx4 v[44:47], v10, s[30:31] offset:112
	global_load_dwordx4 v[48:51], v10, s[30:31] offset:128
	global_load_dwordx4 v[52:55], v10, s[30:31] offset:144
	global_load_dwordx4 v[56:59], v10, s[30:31] offset:160
	global_load_dwordx4 v[60:63], v10, s[30:31] offset:176
	global_load_dwordx4 v[64:67], v10, s[30:31] offset:192
	global_load_dwordx4 v[68:71], v10, s[30:31] offset:208
	global_load_dwordx4 v[72:75], v10, s[30:31] offset:224
	global_load_dwordx4 v[76:79], v10, s[30:31] offset:240
.Lpo_nosr:
	global_load_dword v80, v1, s[6:7]
	global_load_dword v81, v1, s[8:9]
	global_load_dword v82, v1, s[14:15]
	global_load_ushort v83, v2, s[10:11]
	global_load_dword v84, v5, s[12:13]
	s_add_u32 s6, s6, 0x2000
	s_addc_u32 s7, s7, 0
	s_add_u32 s8, s8, 0x2000
	s_addc_u32 s9, s9, 0
	s_add_u32 s14, s14, 0x2000
	s_addc_u32 s15, s15, 0
	s_add_u32 s10, s10, 0x1000
	s_addc_u32 s11, s11, 0
	s_add_u32 s12, s12, 0x80
	s_addc_u32 s13, s13, 0
	global_load_dword v85, v1, s[6:7]
	global_load_dword v86, v1, s[8:9]
	global_load_dword v87, v1, s[14:15]
	global_load_ushort v88, v2, s[10:11]
	global_load_dword v89, v5, s[12:13]
	s_add_u32 s6, s6, 0x2000
	s_addc_u32 s7, s7, 0
	s_add_u32 s8, s8, 0x2000
	s_addc_u32 s9, s9, 0
	s_add_u32 s14, s14, 0x2000
	s_addc_u32 s15, s15, 0
	s_add_u32 s10, s10, 0x1000
	s_addc_u32 s11, s11, 0
	s_add_u32 s12, s12, 0x80
	s_addc_u32 s13, s13, 0
	global_load_dword v90, v1, s[6:7]
	global_load_dword v91, v1, s[8:9]
	global_load_dword v92, v1, s[14:15]
	global_load_ushort v93, v2, s[10:11]
	global_load_dword v94, v5, s[12:13]
	s_add_u32 s6, s6, 0x2000
	s_addc_u32 s7, s7, 0
	s_add_u32 s8, s8, 0x2000
	s_addc_u32 s9, s9, 0
	s_add_u32 s14, s14, 0x2000
	s_addc_u32 s15, s15, 0
	s_add_u32 s10, s10, 0x1000
	s_addc_u32 s11, s11, 0
	s_add_u32 s12, s12, 0x80
	s_addc_u32 s13, s13, 0
	global_load_dword v95, v1, s[6:7]
	global_load_dword v96, v1, s[8:9]
	global_load_dword v97, v1, s[14:15]
	global_load_ushort v98, v2, s[10:11]
	global_load_dword v99, v5, s[12:13]
	s_add_u32 s6, s6, 0x2000
	s_addc_u32 s7, s7, 0
	s_add_u32 s8, s8, 0x2000
	s_addc_u32 s9, s9, 0
	s_add_u32 s14, s14, 0x2000
	s_addc_u32 s15, s15, 0
	s_add_u32 s10, s10, 0x1000
	s_addc_u32 s11, s11, 0
	s_add_u32 s12, s12, 0x80
	s_addc_u32 s13, s13, 0
	global_load_dword v100, v1, s[6:7]
	global_load_dword v101, v1, s[8:9]
	global_load_dword v102, v1, s[14:15]
	global_load_ushort v103, v2, s[10:11]
	global_load_dword v104, v5, s[12:13]
	s_add_u32 s6, s6, 0x2000
	s_addc_u32 s7, s7, 0
	s_add_u32 s8, s8, 0x2000
	s_addc_u32 s9, s9, 0
	s_add_u32 s14, s14, 0x2000
	s_addc_u32 s15, s15, 0
	s_add_u32 s10, s10, 0x1000
	s_addc_u32 s11, s11, 0
	s_add_u32 s12, s12, 0x80
	s_addc_u32 s13, s13, 0
	global_load_dword v105, v1, s[6:7]
	global_load_dword v106, v1, s[8:9]
	global_load_dword v107, v1, s[14:15]
	global_load_ushort v108, v2, s[10:11]
	global_load_dword v109, v5, s[12:13]
	s_add_u32 s6, s6, 0x2000
	s_addc_u32 s7, s7, 0
	s_add_u32 s8, s8, 0x2000
	s_addc_u32 s9, s9, 0
	s_add_u32 s14, s14, 0x2000
	s_addc_u32 s15, s15, 0
	s_add_u32 s10, s10, 0x1000
	s_addc_u32 s11, s11, 0
	s_add_u32 s12, s12, 0x80
	s_addc_u32 s13, s13, 0
	global_load_dword v110, v1, s[6:7]
	global_load_dword v111, v1, s[8:9]
	global_load_dword v112, v1, s[14:15]
	global_load_ushort v113, v2, s[10:11]
	global_load_dword v114, v5, s[12:13]
	s_add_u32 s6, s6, 0x2000
	s_addc_u32 s7, s7, 0
	s_add_u32 s8, s8, 0x2000
	s_addc_u32 s9, s9, 0
	s_add_u32 s14, s14, 0x2000
	s_addc_u32 s15, s15, 0
	s_add_u32 s10, s10, 0x1000
	s_addc_u32 s11, s11, 0
	s_add_u32 s12, s12, 0x80
	s_addc_u32 s13, s13, 0
	global_load_dword v115, v1, s[6:7]
	global_load_dword v116, v1, s[8:9]
	global_load_dword v117, v1, s[14:15]
	global_load_ushort v118, v2, s[10:11]
	global_load_dword v119, v5, s[12:13]
	s_add_u32 s6, s6, 0x2000
	s_addc_u32 s7, s7, 0
	s_add_u32 s8, s8, 0x2000
	s_addc_u32 s9, s9, 0
	s_add_u32 s14, s14, 0x2000
	s_addc_u32 s15, s15, 0
	s_add_u32 s10, s10, 0x1000
	s_addc_u32 s11, s11, 0
	s_add_u32 s12, s12, 0x80
	s_addc_u32 s13, s13, 0
	s_waitcnt vmcnt(0)
	s_mov_b32 s25, 4
; #define LAS __attribute__((address_space(3)))
; __device__ __forceinline__ void rw_post(Frame& F) {
;     ...
;             if (k > 0) {
;                 LAS float* cs = (LAS float*)(F.lds + 131072 + F.wave * 1024);
; #pragma unroll
;                 for (int hf = 0; hf < 2; ++hf) {
; #pragma unroll
;                     for (int q = 0; q < 4; ++q) cs[q * 64 + lane] = cc[4 * hf + q];
;                     asm volatile("s_waitcnt lgkmcnt(0)" ::: "memory");
; #pragma unroll
;                     for (int q = 0; q < 4; ++q) { f32x4 a = (f32x4){0.f, 0.f, 0.f, 0.f};
; #pragma unroll
;                         for (int i = 0; i < 16; ++i) a = __builtin_elementwise_fma(Sr[i], *(const LAS f32x4*)(cs + q * 64 + 4 * i), a);
;                         y[4 * hf + q] += (a[0] + a[1]) + (a[2] + a[3]); }
.Lpo_pair:
	s_cmp_eq_u32 s23, 0
	s_cbranch_scc1 .Lpo_nc1
	ds_write_b32 v3, v82
	ds_write_b32 v3, v87 offset:256
	ds_write_b32 v3, v92 offset:512
	ds_write_b32 v3, v97 offset:768
	s_waitcnt lgkmcnt(0)
	ds_read_b128 v[204:207], v4 offset:0
	ds_read_b128 v[208:211], v4 offset:256
	ds_read_b128 v[212:215], v4 offset:512
	ds_read_b128 v[216:219], v4 offset:768
	ds_read_b128 v[220:223], v4 offset:16
	ds_read_b128 v[224:227], v4 offset:272
	ds_read_b128 v[228:231], v4 offset:528
	ds_read_b128 v[232:235], v4 offset:784
	s_waitcnt lgkmcnt(4)
	v_pk_mul_f32 v[184:185], v[16:17], v[204:205]
	v_pk_mul_f32 v[188:189], v[16:17], v[208:209]
	v_pk_mul_f32 v[192:193], v[16:17], v[212:213]
	v_pk_mul_f32 v[196:197], v[16:17], v[216:217]
	v_pk_mul_f32 v[186:187], v[18:19], v[206:207]
	v_pk_mul_f32 v[190:191], v[18:19], v[210:211]
	v_pk_mul_f32 v[194:195], v[18:19], v[214:215]
	v_pk_mul_f32 v[198:199], v[18:19], v[218:219]
	ds_read_b128 v[204:207], v4 offset:32
	ds_read_b128 v[208:211], v4 offset:288
	ds_read_b128 v[212:215], v4 offset:544
	ds_read_b128 v[216:219], v4 offset:800
	s_waitcnt lgkmcnt(4)
	v_pk_fma_f32 v[184:185], v[20:21], v[220:221], v[184:185]
	v_pk_fma_f32 v[188:189], v[20:21], v[224:225], v[188:189]
	v_pk_fma_f32 v[192:193], v[20:21], v[228:229], v[192:193]
	v_pk_fma_f32 v[196:197], v[20:21], v[232:233], v[196:197]
	v_pk_fma_f32 v[186:187], v[22:23], v[222:223], v[186:187]
	v_pk_fma_f32 v[190:191], v[22:23], v[226:227], v[190:191]
	v_pk_fma_f32 v[194:195], v[22:23], v[230:231], v[194:195]
	v_pk_fma_f32 v[198:199], v[22:23], v[234:235], v[198:199]
	ds_read_b128 v[220:223], v4 offset:48
	ds_read_b128 v[224:227], v4 offset:304
	ds_read_b128 v[228:231], v4 offset:560
	ds_read_b128 v[232:235], v4 offset:816
	s_waitcnt lgkmcnt(4)
	v_pk_fma_f32 v[184:185], v[24:25], v[204:205], v[184:185]
	v_pk_fma_f32 v[188:189], v[24:25], v[208:209], v[188:189]
	v_pk_fma_f32 v[192:193], v[24:25], v[212:213], v[192:193]
	v_pk_fma_f32 v[196:197], v[24:25], v[216:217], v[196:197]
	v_pk_fma_f32 v[186:187], v[26:27], v[206:207], v[186:187]
	v_pk_fma_f32 v[190:191], v[26:27], v[210:211], v[190:191]
	v_pk_fma_f32 v[194:195], v[26:27], v[214:215], v[194:195]
	v_pk_fma_f32 v[198:199], v[26:27], v[218:219], v[198:199]
	ds_read_b128 v[204:207], v4 offset:64
	ds_read_b128 v[208:211], v4 offset:320
	ds_read_b128 v[212:215], v4 offset:576
	ds_read_b128 v[216:219], v4 offset:832
	s_waitcnt lgkmcnt(4)
	v_pk_fma_f32 v[184:185], v[28:29], v[220:221], v[184:185]
	v_pk_fma_f32 v[188:189], v[28:29], v[224:225], v[188:189]
	v_pk_fma_f32 v[192:193], v[28:29], v[228:229], v[192:193]
	v_pk_fma_f32 v[196:197], v[28:29], v[232:233], v[196:197]
	v_pk_fma_f32 v[186:187], v[30:31], v[222:223], v[186:187]
	v_pk_fma_f32 v[190:191], v[30:31], v[226:227], v[190:191]
	v_pk_fma_f32 v[194:195], v[30:31], v[230:231], v[194:195]
	v_pk_fma_f32 v[198:199], v[30:31], v[234:235], v[198:199]
	ds_read_b128 v[220:223], v4 offset:80
	ds_read_b128 v[224:227], v4 offset:336
	ds_read_b128 v[228:231], v4 offset:592
	ds_read_b128 v[232:235], v4 offset:848
	s_waitcnt lgkmcnt(4)
	v_pk_fma_f32 v[184:185], v[32:33], v[204:205], v[184:185]
	v_pk_fma_f32 v[188:189], v[32:33], v[208:209], v[188:189]
	v_pk_fma_f32 v[192:193], v[32:33], v[212:213], v[192:193]
	v_pk_fma_f32 v[196:197], v[32:33], v[216:217], v[196:197]
	v_pk_fma_f32 v[186:187], v[34:35], v[206:207], v[186:187]
	v_pk_fma_f32 v[190:191], v[34:35], v[210:211], v[190:191]
	v_pk_fma_f32 v[194:195], v[34:35], v[214:215], v[194:195]
	v_pk_fma_f32 v[198:199], v[34:35], v[218:219], v[198:199]
	ds_read_b128 v[204:207], v4 offset:96
	ds_read_b128 v[208:211], v4 offset:352
	ds_read_b128 v[212:215], v4 offset:608
	ds_read_b128 v[216:219], v4 offset:864
	s_waitcnt lgkmcnt(4)
	v_pk_fma_f32 v[184:185], v[36:37], v[220:221], v[184:185]
	v_pk_fma_f32 v[188:189], v[36:37], v[224:225], v[188:189]
	v_pk_fma_f32 v[192:193], v[36:37], v[228:229], v[192:193]
	v_pk_fma_f32 v[196:197], v[36:37], v[232:233], v[196:197]
	v_pk_fma_f32 v[186:187], v[38:39], v[222:223], v[186:187]
	v_pk_fma_f32 v[190:191], v[38:39], v[226:227], v[190:191]
	v_pk_fma_f32 v[194:195], v[38:39], v[230:231], v[194:195]
	v_pk_fma_f32 v[198:199], v[38:39], v[234:235], v[198:199]
	ds_read_b128 v[220:223], v4 offset:112
	ds_read_b128 v[224:227], v4 offset:368
	ds_read_b128 v[228:231], v4 offset:624
	ds_read_b128 v[232:235], v4 offset:880
	s_waitcnt lgkmcnt(4)
	v_pk_fma_f32 v[184:185], v[40:41], v[204:205], v[184:185]
	v_pk_fma_f32 v[188:189], v[40:41], v[208:209], v[188:189]
	v_pk_fma_f32 v[192:193], v[40:41], v[212:213], v[192:193]
	v_pk_fma_f32 v[196:197], v[40:41], v[216:217], v[196:197]
	v_pk_fma_f32 v[186:187], v[42:43], v[206:207], v[186:187]
	v_pk_fma_f32 v[190:191], v[42:43], v[210:211], v[190:191]
	v_pk_fma_f32 v[194:195], v[42:43], v[214:215], v[194:195]
	v_pk_fma_f32 v[198:199], v[42:43], v[218:219], v[198:199]
	ds_read_b128 v[204:207], v4 offset:128
	ds_read_b128 v[208:211], v4 offset:384
	ds_read_b128 v[212:215], v4 offset:640
	ds_read_b128 v[216:219], v4 offset:896
	s_waitcnt lgkmcnt(4)
	v_pk_fma_f32 v[184:185], v[44:45], v[220:221], v[184:185]
	v_pk_fma_f32 v[188:189], v[44:45], v[224:225], v[188:189]
	v_pk_fma_f32 v[192:193], v[44:45], v[228:229], v[192:193]
	v_pk_fma_f32 v[196:197], v[44:45], v[232:233], v[196:197]
	v_pk_fma_f32 v[186:187], v[46:47], v[222:223], v[186:187]
	v_pk_fma_f32 v[190:191], v[46:47], v[226:227], v[190:191]
	v_pk_fma_f32 v[194:195], v[46:47], v[230:231], v[194:195]
	v_pk_fma_f32 v[198:199], v[46:47], v[234:235], v[198:199]
	ds_read_b128 v[220:223], v4 offset:144
	ds_read_b128 v[224:227], v4 offset:400
	ds_read_b128 v[228:231], v4 offset:656
	ds_read_b128 v[232:235], v4 offset:912
	s_waitcnt lgkmcnt(4)
; #define LAS __attribute__((address_space(3)))
; __device__ __forceinline__ void rw_post(Frame& F) {
;     ...
;                     for (int q = 0; q < 4; ++q) { f32x4 a = (f32x4){0.f, 0.f, 0.f, 0.f};
; #pragma unroll
;                         for (int i = 0; i < 16; ++i) a = __builtin_elementwise_fma(Sr[i], *(const LAS f32x4*)(cs + q * 64 + 4 * i), a);
;                         y[4 * hf + q] += (a[0] + a[1]) + (a[2] + a[3]); }
;                     asm volatile("s_waitcnt lgkmcnt(0)" ::: "memory"); }
	v_pk_fma_f32 v[184:185], v[48:49], v[204:205], v[184:185]
	v_pk_fma_f32 v[188:189], v[48:49], v[208:209], v[188:189]
	v_pk_fma_f32 v[192:193], v[48:49], v[212:213], v[192:193]
	v_pk_fma_f32 v[196:197], v[48:49], v[216:217], v[196:197]
	v_pk_fma_f32 v[186:187], v[50:51], v[206:207], v[186:187]
	v_pk_fma_f32 v[190:191], v[50:51], v[210:211], v[190:191]
	v_pk_fma_f32 v[194:195], v[50:51], v[214:215], v[194:195]
	v_pk_fma_f32 v[198:199], v[50:51], v[218:219], v[198:199]
	ds_read_b128 v[204:207], v4 offset:160
	ds_read_b128 v[208:211], v4 offset:416
	ds_read_b128 v[212:215], v4 offset:672
	ds_read_b128 v[216:219], v4 offset:928
	s_waitcnt lgkmcnt(4)
	v_pk_fma_f32 v[184:185], v[52:53], v[220:221], v[184:185]
	v_pk_fma_f32 v[188:189], v[52:53], v[224:225], v[188:189]
	v_pk_fma_f32 v[192:193], v[52:53], v[228:229], v[192:193]
	v_pk_fma_f32 v[196:197], v[52:53], v[232:233], v[196:197]
	v_pk_fma_f32 v[186:187], v[54:55], v[222:223], v[186:187]
	v_pk_fma_f32 v[190:191], v[54:55], v[226:227], v[190:191]
	v_pk_fma_f32 v[194:195], v[54:55], v[230:231], v[194:195]
	v_pk_fma_f32 v[198:199], v[54:55], v[234:235], v[198:199]
	ds_read_b128 v[220:223], v4 offset:176
	ds_read_b128 v[224:227], v4 offset:432
	ds_read_b128 v[228:231], v4 offset:688
	ds_read_b128 v[232:235], v4 offset:944
	s_waitcnt lgkmcnt(4)
	v_pk_fma_f32 v[184:185], v[56:57], v[204:205], v[184:185]
	v_pk_fma_f32 v[188:189], v[56:57], v[208:209], v[188:189]
	v_pk_fma_f32 v[192:193], v[56:57], v[212:213], v[192:193]
	v_pk_fma_f32 v[196:197], v[56:57], v[216:217], v[196:197]
	v_pk_fma_f32 v[186:187], v[58:59], v[206:207], v[186:187]
	v_pk_fma_f32 v[190:191], v[58:59], v[210:211], v[190:191]
	v_pk_fma_f32 v[194:195], v[58:59], v[214:215], v[194:195]
	v_pk_fma_f32 v[198:199], v[58:59], v[218:219], v[198:199]
	ds_read_b128 v[204:207], v4 offset:192
	ds_read_b128 v[208:211], v4 offset:448
	ds_read_b128 v[212:215], v4 offset:704
	ds_read_b128 v[216:219], v4 offset:960
	s_waitcnt lgkmcnt(4)
	v_pk_fma_f32 v[184:185], v[60:61], v[220:221], v[184:185]
	v_pk_fma_f32 v[188:189], v[60:61], v[224:225], v[188:189]
	v_pk_fma_f32 v[192:193], v[60:61], v[228:229], v[192:193]
	v_pk_fma_f32 v[196:197], v[60:61], v[232:233], v[196:197]
	v_pk_fma_f32 v[186:187], v[62:63], v[222:223], v[186:187]
	v_pk_fma_f32 v[190:191], v[62:63], v[226:227], v[190:191]
	v_pk_fma_f32 v[194:195], v[62:63], v[230:231], v[194:195]
	v_pk_fma_f32 v[198:199], v[62:63], v[234:235], v[198:199]
	ds_read_b128 v[220:223], v4 offset:208
	ds_read_b128 v[224:227], v4 offset:464
	ds_read_b128 v[228:231], v4 offset:720
	ds_read_b128 v[232:235], v4 offset:976
	s_waitcnt lgkmcnt(4)
	v_pk_fma_f32 v[184:185], v[64:65], v[204:205], v[184:185]
	v_pk_fma_f32 v[188:189], v[64:65], v[208:209], v[188:189]
	v_pk_fma_f32 v[192:193], v[64:65], v[212:213], v[192:193]
	v_pk_fma_f32 v[196:197], v[64:65], v[216:217], v[196:197]
	v_pk_fma_f32 v[186:187], v[66:67], v[206:207], v[186:187]
	v_pk_fma_f32 v[190:191], v[66:67], v[210:211], v[190:191]
	v_pk_fma_f32 v[194:195], v[66:67], v[214:215], v[194:195]
	v_pk_fma_f32 v[198:199], v[66:67], v[218:219], v[198:199]
	ds_read_b128 v[204:207], v4 offset:224
	ds_read_b128 v[208:211], v4 offset:480
	ds_read_b128 v[212:215], v4 offset:736
	ds_read_b128 v[216:219], v4 offset:992
	s_waitcnt lgkmcnt(4)
	v_pk_fma_f32 v[184:185], v[68:69], v[220:221], v[184:185]
	v_pk_fma_f32 v[188:189], v[68:69], v[224:225], v[188:189]
	v_pk_fma_f32 v[192:193], v[68:69], v[228:229], v[192:193]
	v_pk_fma_f32 v[196:197], v[68:69], v[232:233], v[196:197]
	v_pk_fma_f32 v[186:187], v[70:71], v[222:223], v[186:187]
	v_pk_fma_f32 v[190:191], v[70:71], v[226:227], v[190:191]
	v_pk_fma_f32 v[194:195], v[70:71], v[230:231], v[194:195]
	v_pk_fma_f32 v[198:199], v[70:71], v[234:235], v[198:199]
	ds_read_b128 v[220:223], v4 offset:240
	ds_read_b128 v[224:227], v4 offset:496
	ds_read_b128 v[228:231], v4 offset:752
	ds_read_b128 v[232:235], v4 offset:1008
	s_waitcnt lgkmcnt(4)
	v_pk_fma_f32 v[184:185], v[72:73], v[204:205], v[184:185]
	v_pk_fma_f32 v[188:189], v[72:73], v[208:209], v[188:189]
	v_pk_fma_f32 v[192:193], v[72:73], v[212:213], v[192:193]
	v_pk_fma_f32 v[196:197], v[72:73], v[216:217], v[196:197]
	v_pk_fma_f32 v[186:187], v[74:75], v[206:207], v[186:187]
	v_pk_fma_f32 v[190:191], v[74:75], v[210:211], v[190:191]
	v_pk_fma_f32 v[194:195], v[74:75], v[214:215], v[194:195]
	v_pk_fma_f32 v[198:199], v[74:75], v[218:219], v[198:199]
	s_waitcnt lgkmcnt(0)
	v_pk_fma_f32 v[184:185], v[76:77], v[220:221], v[184:185]
	v_pk_fma_f32 v[188:189], v[76:77], v[224:225], v[188:189]
	v_pk_fma_f32 v[192:193], v[76:77], v[228:229], v[192:193]
	v_pk_fma_f32 v[196:197], v[76:77], v[232:233], v[196:197]
	v_pk_fma_f32 v[186:187], v[78:79], v[222:223], v[186:187]
	v_pk_fma_f32 v[190:191], v[78:79], v[226:227], v[190:191]
	v_pk_fma_f32 v[194:195], v[78:79], v[230:231], v[194:195]
	v_pk_fma_f32 v[198:199], v[78:79], v[234:235], v[198:199]
	v_add_f32_e32 v184, v184, v185
	v_add_f32_e32 v188, v188, v189
	v_add_f32_e32 v192, v192, v193
	v_add_f32_e32 v196, v196, v197
	v_add_f32_e32 v186, v186, v187
	v_add_f32_e32 v190, v190, v191
	v_add_f32_e32 v194, v194, v195
	v_add_f32_e32 v198, v198, v199
	v_add_f32_e32 v184, v184, v186
	v_add_f32_e32 v188, v188, v190
	v_add_f32_e32 v192, v192, v194
	v_add_f32_e32 v196, v196, v198
	v_add_f32_e32 v80, v80, v184
	v_add_f32_e32 v85, v85, v188
	v_add_f32_e32 v90, v90, v192
	v_add_f32_e32 v95, v95, v196
; __device__ __forceinline__ float dpp_xor1(float x) { return __builtin_bit_cast(float, __builtin_amdgcn_update_dpp(0, __builtin_bit_cast(int, x), 0xB1, 0xF, 0xF, true)); }
; __device__ __forceinline__ float dpp_xor2(float x) { return __builtin_bit_cast(float, __builtin_amdgcn_update_dpp(0, __builtin_bit_cast(int, x), 0x4E, 0xF, 0xF, true)); }
; __device__ __forceinline__ float dpp_hmir(float x) { return __builtin_bit_cast(float, __builtin_amdgcn_update_dpp(0, __builtin_bit_cast(int, x), 0x141, 0xF, 0xF, true)); }
; __device__ __forceinline__ float dpp_mir(float x)  { return __builtin_bit_cast(float, __builtin_amdgcn_update_dpp(0, __builtin_bit_cast(int, x), 0x140, 0xF, 0xF, true)); }
; __device__ __forceinline__ float red16(float x) { x += dpp_xor1(x); x += dpp_xor2(x); x += dpp_hmir(x); x += dpp_mir(x); return x; }
; __device__ __forceinline__ float wsum(float x) {
;     x = red16(x); const int xi = __builtin_bit_cast(int, x);
;     const float r0 = __builtin_bit_cast(float, __builtin_amdgcn_readlane(xi, 0)), r1 = __builtin_bit_cast(float, __builtin_amdgcn_readlane(xi, 16));
;     const float r2 = __builtin_bit_cast(float, __builtin_amdgcn_readlane(xi, 32)), r3 = __builtin_bit_cast(float, __builtin_amdgcn_readlane(xi, 48));
;     return (r0 + r1) + (r2 + r3);
; __device__ __forceinline__ void rw_post(Frame& F) {
;     ...
;             for (int q = 0; q < 8; ++q) { const int row = rb0 + t0 + q;
;                 const float mean = wsum(y[q]) * (1.f / 64.f); const float dv = y[q] - mean; const float var = wsum(dv * dv) * (1.f / 64.f);
;                 const float yn = dv * (1.f / sqrtf(var + 64e-5f)) * g_ + b_;
.Lpo_nc1:
	v_add_f32_dpp v168, v80, v80 quad_perm:[1,0,3,2] row_mask:0xf bank_mask:0xf bound_ctrl:1
	v_add_f32_dpp v174, v85, v85 quad_perm:[1,0,3,2] row_mask:0xf bank_mask:0xf bound_ctrl:1
	v_add_f32_dpp v241, v90, v90 quad_perm:[1,0,3,2] row_mask:0xf bank_mask:0xf bound_ctrl:1
	v_add_f32_dpp v247, v95, v95 quad_perm:[1,0,3,2] row_mask:0xf bank_mask:0xf bound_ctrl:1
	v_add_f32_dpp v168, v168, v168 quad_perm:[2,3,0,1] row_mask:0xf bank_mask:0xf bound_ctrl:1
	v_add_f32_dpp v174, v174, v174 quad_perm:[2,3,0,1] row_mask:0xf bank_mask:0xf bound_ctrl:1
	v_add_f32_dpp v241, v241, v241 quad_perm:[2,3,0,1] row_mask:0xf bank_mask:0xf bound_ctrl:1
	v_add_f32_dpp v247, v247, v247 quad_perm:[2,3,0,1] row_mask:0xf bank_mask:0xf bound_ctrl:1
	v_add_f32_dpp v168, v168, v168 row_half_mirror row_mask:0xf bank_mask:0xf bound_ctrl:1
	v_add_f32_dpp v174, v174, v174 row_half_mirror row_mask:0xf bank_mask:0xf bound_ctrl:1
	v_add_f32_dpp v241, v241, v241 row_half_mirror row_mask:0xf bank_mask:0xf bound_ctrl:1
	v_add_f32_dpp v247, v247, v247 row_half_mirror row_mask:0xf bank_mask:0xf bound_ctrl:1
	v_add_f32_dpp v168, v168, v168 row_mirror row_mask:0xf bank_mask:0xf bound_ctrl:1
	v_add_f32_dpp v174, v174, v174 row_mirror row_mask:0xf bank_mask:0xf bound_ctrl:1
	v_add_f32_dpp v241, v241, v241 row_mirror row_mask:0xf bank_mask:0xf bound_ctrl:1
	v_add_f32_dpp v247, v247, v247 row_mirror row_mask:0xf bank_mask:0xf bound_ctrl:1
	v_readlane_b32 s36, v168, 16
	v_readlane_b32 s40, v174, 16
	v_readlane_b32 s44, v241, 16
	v_readlane_b32 s48, v247, 16
	v_readlane_b32 s37, v168, 48
	v_readlane_b32 s41, v174, 48
	v_readlane_b32 s45, v241, 48
	v_readlane_b32 s49, v247, 48
	v_readlane_b32 s38, v168, 0
	v_readlane_b32 s42, v174, 0
	v_readlane_b32 s46, v241, 0
	v_readlane_b32 s50, v247, 0
	v_readlane_b32 s39, v168, 32
	v_readlane_b32 s43, v174, 32
	v_readlane_b32 s47, v241, 32
	v_readlane_b32 s51, v247, 32
	v_mov_b32_e32 v168, s36
	v_mov_b32_e32 v174, s40
	v_mov_b32_e32 v241, s44
	v_mov_b32_e32 v247, s48
	v_mov_b32_e32 v169, s37
	v_mov_b32_e32 v175, s41
	v_mov_b32_e32 v242, s45
	v_mov_b32_e32 v248, s49
	v_add_f32_e32 v168, s38, v168
	v_add_f32_e32 v174, s42, v174
	v_add_f32_e32 v241, s46, v241
	v_add_f32_e32 v247, s50, v247
	v_add_f32_e32 v169, s39, v169
	v_add_f32_e32 v175, s43, v175
	v_add_f32_e32 v242, s47, v242
	v_add_f32_e32 v248, s51, v248
	v_add_f32_e32 v168, v168, v169
	v_add_f32_e32 v174, v174, v175
	v_add_f32_e32 v241, v241, v242
	v_add_f32_e32 v247, v247, v248
	v_fmamk_f32 v80, v168, 0xbc800000, v80
	v_fmamk_f32 v85, v174, 0xbc800000, v85
	v_fmamk_f32 v90, v241, 0xbc800000, v90
	v_fmamk_f32 v95, v247, 0xbc800000, v95
	v_mul_f32_e32 v168, v80, v80
	v_mul_f32_e32 v174, v85, v85
	v_mul_f32_e32 v241, v90, v90
	v_mul_f32_e32 v247, v95, v95
	v_mov_b32_dpp v168, v168 quad_perm:[1,0,3,2] row_mask:0xf bank_mask:0xf bound_ctrl:1
	v_mov_b32_dpp v174, v174 quad_perm:[1,0,3,2] row_mask:0xf bank_mask:0xf bound_ctrl:1
	v_mov_b32_dpp v241, v241 quad_perm:[1,0,3,2] row_mask:0xf bank_mask:0xf bound_ctrl:1
	v_mov_b32_dpp v247, v247 quad_perm:[1,0,3,2] row_mask:0xf bank_mask:0xf bound_ctrl:1
	v_fmac_f32_e32 v168, v80, v80
	v_fmac_f32_e32 v174, v85, v85
	v_fmac_f32_e32 v241, v90, v90
	v_fmac_f32_e32 v247, v95, v95
	v_add_f32_dpp v168, v168, v168 quad_perm:[2,3,0,1] row_mask:0xf bank_mask:0xf bound_ctrl:1
	v_add_f32_dpp v174, v174, v174 quad_perm:[2,3,0,1] row_mask:0xf bank_mask:0xf bound_ctrl:1
	v_add_f32_dpp v241, v241, v241 quad_perm:[2,3,0,1] row_mask:0xf bank_mask:0xf bound_ctrl:1
	v_add_f32_dpp v247, v247, v247 quad_perm:[2,3,0,1] row_mask:0xf bank_mask:0xf bound_ctrl:1
	v_add_f32_dpp v168, v168, v168 row_half_mirror row_mask:0xf bank_mask:0xf bound_ctrl:1
	v_add_f32_dpp v174, v174, v174 row_half_mirror row_mask:0xf bank_mask:0xf bound_ctrl:1
	v_add_f32_dpp v241, v241, v241 row_half_mirror row_mask:0xf bank_mask:0xf bound_ctrl:1
	v_add_f32_dpp v247, v247, v247 row_half_mirror row_mask:0xf bank_mask:0xf bound_ctrl:1
	v_add_f32_dpp v168, v168, v168 row_mirror row_mask:0xf bank_mask:0xf bound_ctrl:1
	v_add_f32_dpp v174, v174, v174 row_mirror row_mask:0xf bank_mask:0xf bound_ctrl:1
	v_add_f32_dpp v241, v241, v241 row_mirror row_mask:0xf bank_mask:0xf bound_ctrl:1
	v_add_f32_dpp v247, v247, v247 row_mirror row_mask:0xf bank_mask:0xf bound_ctrl:1
	v_readlane_b32 s36, v168, 16
	v_readlane_b32 s40, v174, 16
	v_readlane_b32 s44, v241, 16
	v_readlane_b32 s48, v247, 16
	v_readlane_b32 s37, v168, 48
	v_readlane_b32 s41, v174, 48
	v_readlane_b32 s45, v241, 48
	v_readlane_b32 s49, v247, 48
	v_readlane_b32 s38, v168, 0
	v_readlane_b32 s42, v174, 0
	v_readlane_b32 s46, v241, 0
	v_readlane_b32 s50, v247, 0
	v_readlane_b32 s39, v168, 32
	v_readlane_b32 s43, v174, 32
	v_readlane_b32 s47, v241, 32
	v_readlane_b32 s51, v247, 32
	v_mov_b32_e32 v168, s36
	v_mov_b32_e32 v174, s40
	v_mov_b32_e32 v241, s44
	v_mov_b32_e32 v247, s48
	v_mov_b32_e32 v169, s37
	v_mov_b32_e32 v175, s41
	v_mov_b32_e32 v242, s45
	v_mov_b32_e32 v248, s49
	v_add_f32_e32 v168, s38, v168
	v_add_f32_e32 v174, s42, v174
	v_add_f32_e32 v241, s46, v241
	v_add_f32_e32 v247, s50, v247
	v_add_f32_e32 v169, s39, v169
	v_add_f32_e32 v175, s43, v175
	v_add_f32_e32 v242, s47, v242
	v_add_f32_e32 v248, s51, v248
	v_add_f32_e32 v168, v168, v169
	v_add_f32_e32 v174, v174, v175
	v_add_f32_e32 v241, v241, v242
	v_add_f32_e32 v247, v247, v248
	v_fmamk_f32 v168, v168, 0x3c800000, v9
	v_fmamk_f32 v174, v174, 0x3c800000, v9
	v_fmamk_f32 v241, v241, 0x3c800000, v9
	v_fmamk_f32 v247, v247, 0x3c800000, v9
	v_mul_f32_e32 v169, 0x4f800000, v168
	v_mul_f32_e32 v175, 0x4f800000, v174
	v_mul_f32_e32 v242, 0x4f800000, v241
	v_mul_f32_e32 v248, 0x4f800000, v247
; __device__ __forceinline__ float bf2f(bf16 x) { return __uint_as_float(((unsigned)x) << 16); }
; __device__ __forceinline__ unsigned f2bf(float f) { return cvt_pk_bf16(f, 0.f) & 0xffffu; }
; #define POST_LD(Y_, V_, G_, R_, C_, t) do { _Pragma("unroll") for (int q = 0; q < 8; ++q) { const size_t o_ = (size_t)((t) + q) * DH; Y_[q] = yp[o_]; V_[q] = vp[o_]; G_[q] = gp[o_]; R_[q] = rp[((t) + q) * 32]; C_[q] = cp[o_]; } } while (0)
; __device__ __forceinline__ void rw_post(Frame& F) {
;     ...
;         POST_LD(y, vv, gg, rk, cc, 0);
;         for (int t0 = 0; t0 < 64; t0 += 8) {
;             float ny[8], nv[8], nr[8], nc[8]; bf16 ng[8];
;             const int tn = t0 + 8 < 64 ? t0 + 8 : t0;
;             POST_LD(ny, nv, ng, nr, nc, tn);
;     ...
;                 const float mean = wsum(y[q]) * (1.f / 64.f); const float dv = y[q] - mean; const float var = wsum(dv * dv) * (1.f / 64.f);
;                 const float yn = dv * (1.f / sqrtf(var + 64e-5f)) * g_ + b_;
;                 OB[(size_t)row * DH + col] = (bf16)f2bf((yn + rk[q] * vv[q]) * bf2f(gg[q])); }
	v_cmp_gt_f32_e64 s[52:53], s68, v168
	v_cmp_gt_f32_e64 s[54:55], s68, v174
	v_cmp_gt_f32_e64 s[56:57], s68, v241
	v_cmp_gt_f32_e64 s[58:59], s68, v247
	v_mov_b32_e32 v170, v168
	v_mov_b32_e32 v176, v174
	v_mov_b32_e32 v243, v241
	v_mov_b32_e32 v249, v247
	v_cndmask_b32_e64 v168, v170, v169, s[52:53]
	v_cndmask_b32_e64 v174, v176, v175, s[54:55]
	v_cndmask_b32_e64 v241, v243, v242, s[56:57]
	v_cndmask_b32_e64 v247, v249, v248, s[58:59]
	v_sqrt_f32_e32 v169, v168
	v_sqrt_f32_e32 v175, v174
	v_sqrt_f32_e32 v242, v241
	v_sqrt_f32_e32 v248, v247
	v_add_u32_e32 v170, -1, v169
	v_add_u32_e32 v176, -1, v175
	v_add_u32_e32 v243, -1, v242
	v_add_u32_e32 v249, -1, v248
	v_fma_f32 v171, -v170, v169, v168
	v_fma_f32 v177, -v176, v175, v174
	v_fma_f32 v244, -v243, v242, v241
	v_fma_f32 v250, -v249, v248, v247
	v_cmp_ge_f32_e64 s[60:61], 0, v171
	v_cmp_ge_f32_e64 s[62:63], 0, v177
	v_cmp_ge_f32_e64 s[64:65], 0, v244
	v_cmp_ge_f32_e64 s[66:67], 0, v250
	v_add_u32_e32 v171, 1, v169
	v_add_u32_e32 v177, 1, v175
	v_add_u32_e32 v244, 1, v242
	v_add_u32_e32 v250, 1, v248
	v_cndmask_b32_e64 v170, v169, v170, s[60:61]
	v_cndmask_b32_e64 v176, v175, v176, s[62:63]
	v_cndmask_b32_e64 v243, v242, v243, s[64:65]
	v_cndmask_b32_e64 v249, v248, v249, s[66:67]
	v_fma_f32 v169, -v171, v169, v168
	v_fma_f32 v175, -v177, v175, v174
	v_fma_f32 v242, -v244, v242, v241
	v_fma_f32 v248, -v250, v248, v247
	v_cmp_lt_f32_e64 s[60:61], 0, v169
	v_cmp_lt_f32_e64 s[62:63], 0, v175
	v_cmp_lt_f32_e64 s[64:65], 0, v242
	v_cmp_lt_f32_e64 s[66:67], 0, v248
	v_cndmask_b32_e64 v169, v170, v171, s[60:61]
	v_cndmask_b32_e64 v175, v176, v177, s[62:63]
	v_cndmask_b32_e64 v242, v243, v244, s[64:65]
	v_cndmask_b32_e64 v248, v249, v250, s[66:67]
	v_mul_f32_e32 v170, 0x37800000, v169
	v_mul_f32_e32 v176, 0x37800000, v175
	v_mul_f32_e32 v243, 0x37800000, v242
	v_mul_f32_e32 v249, 0x37800000, v248
	v_cndmask_b32_e64 v169, v169, v170, s[52:53]
	v_cndmask_b32_e64 v175, v175, v176, s[54:55]
	v_cndmask_b32_e64 v242, v242, v243, s[56:57]
	v_cndmask_b32_e64 v248, v248, v249, s[58:59]
	v_cmp_class_f32_e64 s[60:61], v168, v8
	v_cmp_class_f32_e64 s[62:63], v174, v8
	v_cmp_class_f32_e64 s[64:65], v241, v8
	v_cmp_class_f32_e64 s[66:67], v247, v8
	v_cndmask_b32_e64 v168, v169, v168, s[60:61]
	v_cndmask_b32_e64 v174, v175, v174, s[62:63]
	v_cndmask_b32_e64 v241, v242, v241, s[64:65]
	v_cndmask_b32_e64 v247, v248, v247, s[66:67]
	v_div_scale_f32 v169, s[60:61], v168, v168, 1.0
	v_rcp_f32_e32 v170, v169
	s_nop 0
	v_fma_f32 v171, -v169, v170, 1.0
	v_fmac_f32_e32 v170, v171, v170
	v_div_scale_f32 v171, vcc, 1.0, v168, 1.0
	v_mul_f32_e32 v172, v171, v170
	v_fma_f32 v173, -v169, v172, v171
	v_fmac_f32_e32 v172, v173, v170
	v_fma_f32 v169, -v169, v172, v171
	v_div_fmas_f32 v169, v169, v170, v172
	v_div_fixup_f32 v168, v169, v168, 1.0
	v_div_scale_f32 v175, s[62:63], v174, v174, 1.0
	v_rcp_f32_e32 v176, v175
	s_nop 0
	v_fma_f32 v177, -v175, v176, 1.0
	v_fmac_f32_e32 v176, v177, v176
	v_div_scale_f32 v177, vcc, 1.0, v174, 1.0
	v_mul_f32_e32 v236, v177, v176
	v_fma_f32 v237, -v175, v236, v177
	v_fmac_f32_e32 v236, v237, v176
	v_fma_f32 v175, -v175, v236, v177
	v_div_fmas_f32 v175, v175, v176, v236
	v_div_fixup_f32 v174, v175, v174, 1.0
	v_div_scale_f32 v242, s[64:65], v241, v241, 1.0
	v_rcp_f32_e32 v243, v242
	s_nop 0
	v_fma_f32 v244, -v242, v243, 1.0
	v_fmac_f32_e32 v243, v244, v243
	v_div_scale_f32 v244, vcc, 1.0, v241, 1.0
	v_mul_f32_e32 v245, v244, v243
	v_fma_f32 v246, -v242, v245, v244
	v_fmac_f32_e32 v245, v246, v243
	v_fma_f32 v242, -v242, v245, v244
	v_div_fmas_f32 v242, v242, v243, v245
	v_div_fixup_f32 v241, v242, v241, 1.0
	v_div_scale_f32 v248, s[66:67], v247, v247, 1.0
	v_rcp_f32_e32 v249, v248
	s_nop 0
	v_fma_f32 v250, -v248, v249, 1.0
	v_fmac_f32_e32 v249, v250, v249
	v_div_scale_f32 v250, vcc, 1.0, v247, 1.0
	v_mul_f32_e32 v251, v250, v249
	v_fma_f32 v252, -v248, v251, v250
	v_fmac_f32_e32 v251, v252, v249
	v_fma_f32 v248, -v248, v251, v250
	v_div_fmas_f32 v248, v248, v249, v251
	v_div_fixup_f32 v247, v248, v247, 1.0
	v_mul_f32_e32 v80, v80, v168
	v_mul_f32_e32 v85, v85, v174
	v_mul_f32_e32 v90, v90, v241
	v_mul_f32_e32 v95, v95, v247
	v_lshlrev_b32_e32 v83, 16, v83
	v_lshlrev_b32_e32 v88, 16, v88
	v_lshlrev_b32_e32 v93, 16, v93
	v_lshlrev_b32_e32 v98, 16, v98
	v_fma_f32 v80, v6, v80, v7
	v_fma_f32 v85, v6, v85, v7
	v_fma_f32 v90, v6, v90, v7
	v_fma_f32 v95, v6, v95, v7
	v_fmac_f32_e32 v80, v84, v81
	v_fmac_f32_e32 v85, v89, v86
	v_fmac_f32_e32 v90, v94, v91
	v_fmac_f32_e32 v95, v99, v96
	v_mul_f32_e32 v80, v80, v83
	v_mul_f32_e32 v85, v85, v88
	v_mul_f32_e32 v90, v90, v93
	v_mul_f32_e32 v95, v95, v98
	v_cvt_pk_bf16_f32 v169, v80, v80
	v_cvt_pk_bf16_f32 v175, v85, v85
	v_cvt_pk_bf16_f32 v242, v90, v90
	v_cvt_pk_bf16_f32 v248, v95, v95
	global_store_short v2, v169, s[28:29]
	s_add_u32 s28, s28, 0x1000
	s_addc_u32 s29, s29, 0
	global_store_short v2, v175, s[28:29]
	s_add_u32 s28, s28, 0x1000
	s_addc_u32 s29, s29, 0
	global_store_short v2, v242, s[28:29]
	s_add_u32 s28, s28, 0x1000
	s_addc_u32 s29, s29, 0
	global_store_short v2, v248, s[28:29]
	s_add_u32 s28, s28, 0x1000
	s_addc_u32 s29, s29, 0
	global_load_dword v120, v1, s[6:7]
	global_load_dword v121, v1, s[8:9]
	global_load_dword v122, v1, s[14:15]
	global_load_ushort v123, v2, s[10:11]
	global_load_dword v124, v5, s[12:13]
	s_add_u32 s6, s6, 0x2000
	s_addc_u32 s7, s7, 0
	s_add_u32 s8, s8, 0x2000
	s_addc_u32 s9, s9, 0
	s_add_u32 s14, s14, 0x2000
	s_addc_u32 s15, s15, 0
	s_add_u32 s10, s10, 0x1000
	s_addc_u32 s11, s11, 0
	s_add_u32 s12, s12, 0x80
	s_addc_u32 s13, s13, 0
	global_load_dword v125, v1, s[6:7]
	global_load_dword v126, v1, s[8:9]
; #define LAS __attribute__((address_space(3)))
; #define POST_LD(Y_, V_, G_, R_, C_, t) do { _Pragma("unroll") for (int q = 0; q < 8; ++q) { const size_t o_ = (size_t)((t) + q) * DH; Y_[q] = yp[o_]; V_[q] = vp[o_]; G_[q] = gp[o_]; R_[q] = rp[((t) + q) * 32]; C_[q] = cp[o_]; } } while (0)
; __device__ __forceinline__ void rw_post(Frame& F) {
;     ...
;         POST_LD(y, vv, gg, rk, cc, 0);
;         for (int t0 = 0; t0 < 64; t0 += 8) {
;             float ny[8], nv[8], nr[8], nc[8]; bf16 ng[8];
;             const int tn = t0 + 8 < 64 ? t0 + 8 : t0;
;             POST_LD(ny, nv, ng, nr, nc, tn);
;             if (k > 0) {
;                 LAS float* cs = (LAS float*)(F.lds + 131072 + F.wave * 1024);
; #pragma unroll
;                 for (int hf = 0; hf < 2; ++hf) {
; #pragma unroll
;                     for (int q = 0; q < 4; ++q) cs[q * 64 + lane] = cc[4 * hf + q];
;                     asm volatile("s_waitcnt lgkmcnt(0)" ::: "memory");
; #pragma unroll
;                     for (int q = 0; q < 4; ++q) { f32x4 a = (f32x4){0.f, 0.f, 0.f, 0.f};
; #pragma unroll
;                         for (int i = 0; i < 16; ++i) a = __builtin_elementwise_fma(Sr[i], *(const LAS f32x4*)(cs + q * 64 + 4 * i), a);
;                         y[4 * hf + q] += (a[0] + a[1]) + (a[2] + a[3]); }
	global_load_dword v127, v1, s[14:15]
	global_load_ushort v128, v2, s[10:11]
	global_load_dword v129, v5, s[12:13]
	s_add_u32 s6, s6, 0x2000
	s_addc_u32 s7, s7, 0
	s_add_u32 s8, s8, 0x2000
	s_addc_u32 s9, s9, 0
	s_add_u32 s14, s14, 0x2000
	s_addc_u32 s15, s15, 0
	s_add_u32 s10, s10, 0x1000
	s_addc_u32 s11, s11, 0
	s_add_u32 s12, s12, 0x80
	s_addc_u32 s13, s13, 0
	global_load_dword v130, v1, s[6:7]
	global_load_dword v131, v1, s[8:9]
	global_load_dword v132, v1, s[14:15]
	global_load_ushort v133, v2, s[10:11]
	global_load_dword v134, v5, s[12:13]
	s_add_u32 s6, s6, 0x2000
	s_addc_u32 s7, s7, 0
	s_add_u32 s8, s8, 0x2000
	s_addc_u32 s9, s9, 0
	s_add_u32 s14, s14, 0x2000
	s_addc_u32 s15, s15, 0
	s_add_u32 s10, s10, 0x1000
	s_addc_u32 s11, s11, 0
	s_add_u32 s12, s12, 0x80
	s_addc_u32 s13, s13, 0
	global_load_dword v135, v1, s[6:7]
	global_load_dword v136, v1, s[8:9]
	global_load_dword v137, v1, s[14:15]
	global_load_ushort v138, v2, s[10:11]
	global_load_dword v139, v5, s[12:13]
	s_add_u32 s6, s6, 0x2000
	s_addc_u32 s7, s7, 0
	s_add_u32 s8, s8, 0x2000
	s_addc_u32 s9, s9, 0
	s_add_u32 s14, s14, 0x2000
	s_addc_u32 s15, s15, 0
	s_add_u32 s10, s10, 0x1000
	s_addc_u32 s11, s11, 0
	s_add_u32 s12, s12, 0x80
	s_addc_u32 s13, s13, 0
	global_load_dword v140, v1, s[6:7]
	global_load_dword v141, v1, s[8:9]
	global_load_dword v142, v1, s[14:15]
	global_load_ushort v143, v2, s[10:11]
	global_load_dword v144, v5, s[12:13]
	s_add_u32 s6, s6, 0x2000
	s_addc_u32 s7, s7, 0
	s_add_u32 s8, s8, 0x2000
	s_addc_u32 s9, s9, 0
	s_add_u32 s14, s14, 0x2000
	s_addc_u32 s15, s15, 0
	s_add_u32 s10, s10, 0x1000
	s_addc_u32 s11, s11, 0
	s_add_u32 s12, s12, 0x80
	s_addc_u32 s13, s13, 0
	global_load_dword v145, v1, s[6:7]
	global_load_dword v146, v1, s[8:9]
	global_load_dword v147, v1, s[14:15]
	global_load_ushort v148, v2, s[10:11]
	global_load_dword v149, v5, s[12:13]
	s_add_u32 s6, s6, 0x2000
	s_addc_u32 s7, s7, 0
	s_add_u32 s8, s8, 0x2000
	s_addc_u32 s9, s9, 0
	s_add_u32 s14, s14, 0x2000
	s_addc_u32 s15, s15, 0
	s_add_u32 s10, s10, 0x1000
	s_addc_u32 s11, s11, 0
	s_add_u32 s12, s12, 0x80
	s_addc_u32 s13, s13, 0
	global_load_dword v150, v1, s[6:7]
	global_load_dword v151, v1, s[8:9]
	global_load_dword v152, v1, s[14:15]
	global_load_ushort v153, v2, s[10:11]
	global_load_dword v154, v5, s[12:13]
	s_add_u32 s6, s6, 0x2000
	s_addc_u32 s7, s7, 0
	s_add_u32 s8, s8, 0x2000
	s_addc_u32 s9, s9, 0
	s_add_u32 s14, s14, 0x2000
	s_addc_u32 s15, s15, 0
	s_add_u32 s10, s10, 0x1000
	s_addc_u32 s11, s11, 0
	s_add_u32 s12, s12, 0x80
	s_addc_u32 s13, s13, 0
	global_load_dword v155, v1, s[6:7]
	global_load_dword v156, v1, s[8:9]
	global_load_dword v157, v1, s[14:15]
	global_load_ushort v158, v2, s[10:11]
	global_load_dword v159, v5, s[12:13]
	s_add_u32 s6, s6, 0x2000
	s_addc_u32 s7, s7, 0
	s_add_u32 s8, s8, 0x2000
	s_addc_u32 s9, s9, 0
	s_add_u32 s14, s14, 0x2000
	s_addc_u32 s15, s15, 0
	s_add_u32 s10, s10, 0x1000
	s_addc_u32 s11, s11, 0
	s_add_u32 s12, s12, 0x80
	s_addc_u32 s13, s13, 0
	s_cmp_eq_u32 s23, 0
	s_cbranch_scc1 .Lpo_nc2
	ds_write_b32 v3, v102
	ds_write_b32 v3, v107 offset:256
	ds_write_b32 v3, v112 offset:512
	ds_write_b32 v3, v117 offset:768
	s_waitcnt lgkmcnt(0)
	ds_read_b128 v[204:207], v4 offset:0
	ds_read_b128 v[208:211], v4 offset:256
	ds_read_b128 v[212:215], v4 offset:512
	ds_read_b128 v[216:219], v4 offset:768
	ds_read_b128 v[220:223], v4 offset:16
	ds_read_b128 v[224:227], v4 offset:272
	ds_read_b128 v[228:231], v4 offset:528
	ds_read_b128 v[232:235], v4 offset:784
	s_waitcnt lgkmcnt(4)
	v_pk_mul_f32 v[184:185], v[16:17], v[204:205]
	v_pk_mul_f32 v[188:189], v[16:17], v[208:209]
	v_pk_mul_f32 v[192:193], v[16:17], v[212:213]
	v_pk_mul_f32 v[196:197], v[16:17], v[216:217]
	v_pk_mul_f32 v[186:187], v[18:19], v[206:207]
	v_pk_mul_f32 v[190:191], v[18:19], v[210:211]
	v_pk_mul_f32 v[194:195], v[18:19], v[214:215]
	v_pk_mul_f32 v[198:199], v[18:19], v[218:219]
	ds_read_b128 v[204:207], v4 offset:32
	ds_read_b128 v[208:211], v4 offset:288
	ds_read_b128 v[212:215], v4 offset:544
	ds_read_b128 v[216:219], v4 offset:800
	s_waitcnt lgkmcnt(4)
	v_pk_fma_f32 v[184:185], v[20:21], v[220:221], v[184:185]
	v_pk_fma_f32 v[188:189], v[20:21], v[224:225], v[188:189]
	v_pk_fma_f32 v[192:193], v[20:21], v[228:229], v[192:193]
	v_pk_fma_f32 v[196:197], v[20:21], v[232:233], v[196:197]
	v_pk_fma_f32 v[186:187], v[22:23], v[222:223], v[186:187]
	v_pk_fma_f32 v[190:191], v[22:23], v[226:227], v[190:191]
	v_pk_fma_f32 v[194:195], v[22:23], v[230:231], v[194:195]
	v_pk_fma_f32 v[198:199], v[22:23], v[234:235], v[198:199]
	ds_read_b128 v[220:223], v4 offset:48
	ds_read_b128 v[224:227], v4 offset:304
	ds_read_b128 v[228:231], v4 offset:560
	ds_read_b128 v[232:235], v4 offset:816
	s_waitcnt lgkmcnt(4)
	v_pk_fma_f32 v[184:185], v[24:25], v[204:205], v[184:185]
	v_pk_fma_f32 v[188:189], v[24:25], v[208:209], v[188:189]
	v_pk_fma_f32 v[192:193], v[24:25], v[212:213], v[192:193]
	v_pk_fma_f32 v[196:197], v[24:25], v[216:217], v[196:197]
	v_pk_fma_f32 v[186:187], v[26:27], v[206:207], v[186:187]
	v_pk_fma_f32 v[190:191], v[26:27], v[210:211], v[190:191]
	v_pk_fma_f32 v[194:195], v[26:27], v[214:215], v[194:195]
	v_pk_fma_f32 v[198:199], v[26:27], v[218:219], v[198:199]
	ds_read_b128 v[204:207], v4 offset:64
	ds_read_b128 v[208:211], v4 offset:320
	ds_read_b128 v[212:215], v4 offset:576
	ds_read_b128 v[216:219], v4 offset:832
	s_waitcnt lgkmcnt(4)
; #define LAS __attribute__((address_space(3)))
; __device__ __forceinline__ void rw_post(Frame& F) {
;     ...
;                     for (int q = 0; q < 4; ++q) { f32x4 a = (f32x4){0.f, 0.f, 0.f, 0.f};
; #pragma unroll
;                         for (int i = 0; i < 16; ++i) a = __builtin_elementwise_fma(Sr[i], *(const LAS f32x4*)(cs + q * 64 + 4 * i), a);
;                         y[4 * hf + q] += (a[0] + a[1]) + (a[2] + a[3]); }
	v_pk_fma_f32 v[184:185], v[28:29], v[220:221], v[184:185]
	v_pk_fma_f32 v[188:189], v[28:29], v[224:225], v[188:189]
	v_pk_fma_f32 v[192:193], v[28:29], v[228:229], v[192:193]
	v_pk_fma_f32 v[196:197], v[28:29], v[232:233], v[196:197]
	v_pk_fma_f32 v[186:187], v[30:31], v[222:223], v[186:187]
	v_pk_fma_f32 v[190:191], v[30:31], v[226:227], v[190:191]
	v_pk_fma_f32 v[194:195], v[30:31], v[230:231], v[194:195]
	v_pk_fma_f32 v[198:199], v[30:31], v[234:235], v[198:199]
	ds_read_b128 v[220:223], v4 offset:80
	ds_read_b128 v[224:227], v4 offset:336
	ds_read_b128 v[228:231], v4 offset:592
	ds_read_b128 v[232:235], v4 offset:848
	s_waitcnt lgkmcnt(4)
	v_pk_fma_f32 v[184:185], v[32:33], v[204:205], v[184:185]
	v_pk_fma_f32 v[188:189], v[32:33], v[208:209], v[188:189]
	v_pk_fma_f32 v[192:193], v[32:33], v[212:213], v[192:193]
	v_pk_fma_f32 v[196:197], v[32:33], v[216:217], v[196:197]
	v_pk_fma_f32 v[186:187], v[34:35], v[206:207], v[186:187]
	v_pk_fma_f32 v[190:191], v[34:35], v[210:211], v[190:191]
	v_pk_fma_f32 v[194:195], v[34:35], v[214:215], v[194:195]
	v_pk_fma_f32 v[198:199], v[34:35], v[218:219], v[198:199]
	ds_read_b128 v[204:207], v4 offset:96
	ds_read_b128 v[208:211], v4 offset:352
	ds_read_b128 v[212:215], v4 offset:608
	ds_read_b128 v[216:219], v4 offset:864
	s_waitcnt lgkmcnt(4)
	v_pk_fma_f32 v[184:185], v[36:37], v[220:221], v[184:185]
	v_pk_fma_f32 v[188:189], v[36:37], v[224:225], v[188:189]
	v_pk_fma_f32 v[192:193], v[36:37], v[228:229], v[192:193]
	v_pk_fma_f32 v[196:197], v[36:37], v[232:233], v[196:197]
	v_pk_fma_f32 v[186:187], v[38:39], v[222:223], v[186:187]
	v_pk_fma_f32 v[190:191], v[38:39], v[226:227], v[190:191]
	v_pk_fma_f32 v[194:195], v[38:39], v[230:231], v[194:195]
	v_pk_fma_f32 v[198:199], v[38:39], v[234:235], v[198:199]
	ds_read_b128 v[220:223], v4 offset:112
	ds_read_b128 v[224:227], v4 offset:368
	ds_read_b128 v[228:231], v4 offset:624
	ds_read_b128 v[232:235], v4 offset:880
	s_waitcnt lgkmcnt(4)
	v_pk_fma_f32 v[184:185], v[40:41], v[204:205], v[184:185]
	v_pk_fma_f32 v[188:189], v[40:41], v[208:209], v[188:189]
	v_pk_fma_f32 v[192:193], v[40:41], v[212:213], v[192:193]
	v_pk_fma_f32 v[196:197], v[40:41], v[216:217], v[196:197]
	v_pk_fma_f32 v[186:187], v[42:43], v[206:207], v[186:187]
	v_pk_fma_f32 v[190:191], v[42:43], v[210:211], v[190:191]
	v_pk_fma_f32 v[194:195], v[42:43], v[214:215], v[194:195]
	v_pk_fma_f32 v[198:199], v[42:43], v[218:219], v[198:199]
	ds_read_b128 v[204:207], v4 offset:128
	ds_read_b128 v[208:211], v4 offset:384
	ds_read_b128 v[212:215], v4 offset:640
	ds_read_b128 v[216:219], v4 offset:896
	s_waitcnt lgkmcnt(4)
	v_pk_fma_f32 v[184:185], v[44:45], v[220:221], v[184:185]
	v_pk_fma_f32 v[188:189], v[44:45], v[224:225], v[188:189]
	v_pk_fma_f32 v[192:193], v[44:45], v[228:229], v[192:193]
	v_pk_fma_f32 v[196:197], v[44:45], v[232:233], v[196:197]
	v_pk_fma_f32 v[186:187], v[46:47], v[222:223], v[186:187]
	v_pk_fma_f32 v[190:191], v[46:47], v[226:227], v[190:191]
	v_pk_fma_f32 v[194:195], v[46:47], v[230:231], v[194:195]
	v_pk_fma_f32 v[198:199], v[46:47], v[234:235], v[198:199]
	ds_read_b128 v[220:223], v4 offset:144
	ds_read_b128 v[224:227], v4 offset:400
	ds_read_b128 v[228:231], v4 offset:656
	ds_read_b128 v[232:235], v4 offset:912
	s_waitcnt lgkmcnt(4)
	v_pk_fma_f32 v[184:185], v[48:49], v[204:205], v[184:185]
	v_pk_fma_f32 v[188:189], v[48:49], v[208:209], v[188:189]
	v_pk_fma_f32 v[192:193], v[48:49], v[212:213], v[192:193]
	v_pk_fma_f32 v[196:197], v[48:49], v[216:217], v[196:197]
	v_pk_fma_f32 v[186:187], v[50:51], v[206:207], v[186:187]
	v_pk_fma_f32 v[190:191], v[50:51], v[210:211], v[190:191]
	v_pk_fma_f32 v[194:195], v[50:51], v[214:215], v[194:195]
	v_pk_fma_f32 v[198:199], v[50:51], v[218:219], v[198:199]
	ds_read_b128 v[204:207], v4 offset:160
	ds_read_b128 v[208:211], v4 offset:416
	ds_read_b128 v[212:215], v4 offset:672
	ds_read_b128 v[216:219], v4 offset:928
	s_waitcnt lgkmcnt(4)
	v_pk_fma_f32 v[184:185], v[52:53], v[220:221], v[184:185]
	v_pk_fma_f32 v[188:189], v[52:53], v[224:225], v[188:189]
	v_pk_fma_f32 v[192:193], v[52:53], v[228:229], v[192:193]
	v_pk_fma_f32 v[196:197], v[52:53], v[232:233], v[196:197]
	v_pk_fma_f32 v[186:187], v[54:55], v[222:223], v[186:187]
	v_pk_fma_f32 v[190:191], v[54:55], v[226:227], v[190:191]
	v_pk_fma_f32 v[194:195], v[54:55], v[230:231], v[194:195]
	v_pk_fma_f32 v[198:199], v[54:55], v[234:235], v[198:199]
	ds_read_b128 v[220:223], v4 offset:176
	ds_read_b128 v[224:227], v4 offset:432
	ds_read_b128 v[228:231], v4 offset:688
	ds_read_b128 v[232:235], v4 offset:944
	s_waitcnt lgkmcnt(4)
	v_pk_fma_f32 v[184:185], v[56:57], v[204:205], v[184:185]
	v_pk_fma_f32 v[188:189], v[56:57], v[208:209], v[188:189]
	v_pk_fma_f32 v[192:193], v[56:57], v[212:213], v[192:193]
	v_pk_fma_f32 v[196:197], v[56:57], v[216:217], v[196:197]
	v_pk_fma_f32 v[186:187], v[58:59], v[206:207], v[186:187]
	v_pk_fma_f32 v[190:191], v[58:59], v[210:211], v[190:191]
	v_pk_fma_f32 v[194:195], v[58:59], v[214:215], v[194:195]
	v_pk_fma_f32 v[198:199], v[58:59], v[218:219], v[198:199]
	ds_read_b128 v[204:207], v4 offset:192
	ds_read_b128 v[208:211], v4 offset:448
	ds_read_b128 v[212:215], v4 offset:704
	ds_read_b128 v[216:219], v4 offset:960
	s_waitcnt lgkmcnt(4)
	v_pk_fma_f32 v[184:185], v[60:61], v[220:221], v[184:185]
	v_pk_fma_f32 v[188:189], v[60:61], v[224:225], v[188:189]
	v_pk_fma_f32 v[192:193], v[60:61], v[228:229], v[192:193]
	v_pk_fma_f32 v[196:197], v[60:61], v[232:233], v[196:197]
	v_pk_fma_f32 v[186:187], v[62:63], v[222:223], v[186:187]
	v_pk_fma_f32 v[190:191], v[62:63], v[226:227], v[190:191]
	v_pk_fma_f32 v[194:195], v[62:63], v[230:231], v[194:195]
	v_pk_fma_f32 v[198:199], v[62:63], v[234:235], v[198:199]
	ds_read_b128 v[220:223], v4 offset:208
	ds_read_b128 v[224:227], v4 offset:464
	ds_read_b128 v[228:231], v4 offset:720
	ds_read_b128 v[232:235], v4 offset:976
	s_waitcnt lgkmcnt(4)
; #define LAS __attribute__((address_space(3)))
; __device__ __forceinline__ void rw_post(Frame& F) {
;     ...
;                     for (int q = 0; q < 4; ++q) { f32x4 a = (f32x4){0.f, 0.f, 0.f, 0.f};
; #pragma unroll
;                         for (int i = 0; i < 16; ++i) a = __builtin_elementwise_fma(Sr[i], *(const LAS f32x4*)(cs + q * 64 + 4 * i), a);
;                         y[4 * hf + q] += (a[0] + a[1]) + (a[2] + a[3]); }
;                     asm volatile("s_waitcnt lgkmcnt(0)" ::: "memory"); }
;             }
; #pragma unroll
;             for (int q = 0; q < 8; ++q) { const int row = rb0 + t0 + q;
;                 const float mean = wsum(y[q]) * (1.f / 64.f); const float dv = y[q] - mean; const float var = wsum(dv * dv) * (1.f / 64.f);
;                 const float yn = dv * (1.f / sqrtf(var + 64e-5f)) * g_ + b_;
	v_pk_fma_f32 v[184:185], v[64:65], v[204:205], v[184:185]
	v_pk_fma_f32 v[188:189], v[64:65], v[208:209], v[188:189]
	v_pk_fma_f32 v[192:193], v[64:65], v[212:213], v[192:193]
	v_pk_fma_f32 v[196:197], v[64:65], v[216:217], v[196:197]
	v_pk_fma_f32 v[186:187], v[66:67], v[206:207], v[186:187]
	v_pk_fma_f32 v[190:191], v[66:67], v[210:211], v[190:191]
	v_pk_fma_f32 v[194:195], v[66:67], v[214:215], v[194:195]
	v_pk_fma_f32 v[198:199], v[66:67], v[218:219], v[198:199]
	ds_read_b128 v[204:207], v4 offset:224
	ds_read_b128 v[208:211], v4 offset:480
	ds_read_b128 v[212:215], v4 offset:736
	ds_read_b128 v[216:219], v4 offset:992
	s_waitcnt lgkmcnt(4)
	v_pk_fma_f32 v[184:185], v[68:69], v[220:221], v[184:185]
	v_pk_fma_f32 v[188:189], v[68:69], v[224:225], v[188:189]
	v_pk_fma_f32 v[192:193], v[68:69], v[228:229], v[192:193]
	v_pk_fma_f32 v[196:197], v[68:69], v[232:233], v[196:197]
	v_pk_fma_f32 v[186:187], v[70:71], v[222:223], v[186:187]
	v_pk_fma_f32 v[190:191], v[70:71], v[226:227], v[190:191]
	v_pk_fma_f32 v[194:195], v[70:71], v[230:231], v[194:195]
	v_pk_fma_f32 v[198:199], v[70:71], v[234:235], v[198:199]
	ds_read_b128 v[220:223], v4 offset:240
	ds_read_b128 v[224:227], v4 offset:496
	ds_read_b128 v[228:231], v4 offset:752
	ds_read_b128 v[232:235], v4 offset:1008
	s_waitcnt lgkmcnt(4)
	v_pk_fma_f32 v[184:185], v[72:73], v[204:205], v[184:185]
	v_pk_fma_f32 v[188:189], v[72:73], v[208:209], v[188:189]
	v_pk_fma_f32 v[192:193], v[72:73], v[212:213], v[192:193]
	v_pk_fma_f32 v[196:197], v[72:73], v[216:217], v[196:197]
	v_pk_fma_f32 v[186:187], v[74:75], v[206:207], v[186:187]
	v_pk_fma_f32 v[190:191], v[74:75], v[210:211], v[190:191]
	v_pk_fma_f32 v[194:195], v[74:75], v[214:215], v[194:195]
	v_pk_fma_f32 v[198:199], v[74:75], v[218:219], v[198:199]
	s_waitcnt lgkmcnt(0)
	v_pk_fma_f32 v[184:185], v[76:77], v[220:221], v[184:185]
	v_pk_fma_f32 v[188:189], v[76:77], v[224:225], v[188:189]
	v_pk_fma_f32 v[192:193], v[76:77], v[228:229], v[192:193]
	v_pk_fma_f32 v[196:197], v[76:77], v[232:233], v[196:197]
	v_pk_fma_f32 v[186:187], v[78:79], v[222:223], v[186:187]
	v_pk_fma_f32 v[190:191], v[78:79], v[226:227], v[190:191]
	v_pk_fma_f32 v[194:195], v[78:79], v[230:231], v[194:195]
	v_pk_fma_f32 v[198:199], v[78:79], v[234:235], v[198:199]
	v_add_f32_e32 v184, v184, v185
	v_add_f32_e32 v188, v188, v189
	v_add_f32_e32 v192, v192, v193
	v_add_f32_e32 v196, v196, v197
	v_add_f32_e32 v186, v186, v187
	v_add_f32_e32 v190, v190, v191
	v_add_f32_e32 v194, v194, v195
	v_add_f32_e32 v198, v198, v199
	v_add_f32_e32 v184, v184, v186
	v_add_f32_e32 v188, v188, v190
	v_add_f32_e32 v192, v192, v194
	v_add_f32_e32 v196, v196, v198
	v_add_f32_e32 v100, v100, v184
	v_add_f32_e32 v105, v105, v188
	v_add_f32_e32 v110, v110, v192
	v_add_f32_e32 v115, v115, v196
.Lpo_nc2:
	v_add_f32_dpp v168, v100, v100 quad_perm:[1,0,3,2] row_mask:0xf bank_mask:0xf bound_ctrl:1
	v_add_f32_dpp v174, v105, v105 quad_perm:[1,0,3,2] row_mask:0xf bank_mask:0xf bound_ctrl:1
	v_add_f32_dpp v241, v110, v110 quad_perm:[1,0,3,2] row_mask:0xf bank_mask:0xf bound_ctrl:1
	v_add_f32_dpp v247, v115, v115 quad_perm:[1,0,3,2] row_mask:0xf bank_mask:0xf bound_ctrl:1
	v_add_f32_dpp v168, v168, v168 quad_perm:[2,3,0,1] row_mask:0xf bank_mask:0xf bound_ctrl:1
	v_add_f32_dpp v174, v174, v174 quad_perm:[2,3,0,1] row_mask:0xf bank_mask:0xf bound_ctrl:1
	v_add_f32_dpp v241, v241, v241 quad_perm:[2,3,0,1] row_mask:0xf bank_mask:0xf bound_ctrl:1
	v_add_f32_dpp v247, v247, v247 quad_perm:[2,3,0,1] row_mask:0xf bank_mask:0xf bound_ctrl:1
	v_add_f32_dpp v168, v168, v168 row_half_mirror row_mask:0xf bank_mask:0xf bound_ctrl:1
	v_add_f32_dpp v174, v174, v174 row_half_mirror row_mask:0xf bank_mask:0xf bound_ctrl:1
	v_add_f32_dpp v241, v241, v241 row_half_mirror row_mask:0xf bank_mask:0xf bound_ctrl:1
	v_add_f32_dpp v247, v247, v247 row_half_mirror row_mask:0xf bank_mask:0xf bound_ctrl:1
	v_add_f32_dpp v168, v168, v168 row_mirror row_mask:0xf bank_mask:0xf bound_ctrl:1
	v_add_f32_dpp v174, v174, v174 row_mirror row_mask:0xf bank_mask:0xf bound_ctrl:1
	v_add_f32_dpp v241, v241, v241 row_mirror row_mask:0xf bank_mask:0xf bound_ctrl:1
	v_add_f32_dpp v247, v247, v247 row_mirror row_mask:0xf bank_mask:0xf bound_ctrl:1
	v_readlane_b32 s36, v168, 16
	v_readlane_b32 s40, v174, 16
	v_readlane_b32 s44, v241, 16
	v_readlane_b32 s48, v247, 16
	v_readlane_b32 s37, v168, 48
	v_readlane_b32 s41, v174, 48
	v_readlane_b32 s45, v241, 48
	v_readlane_b32 s49, v247, 48
	v_readlane_b32 s38, v168, 0
	v_readlane_b32 s42, v174, 0
	v_readlane_b32 s46, v241, 0
	v_readlane_b32 s50, v247, 0
	v_readlane_b32 s39, v168, 32
	v_readlane_b32 s43, v174, 32
	v_readlane_b32 s47, v241, 32
	v_readlane_b32 s51, v247, 32
	v_mov_b32_e32 v168, s36
	v_mov_b32_e32 v174, s40
	v_mov_b32_e32 v241, s44
	v_mov_b32_e32 v247, s48
	v_mov_b32_e32 v169, s37
	v_mov_b32_e32 v175, s41
	v_mov_b32_e32 v242, s45
	v_mov_b32_e32 v248, s49
	v_add_f32_e32 v168, s38, v168
	v_add_f32_e32 v174, s42, v174
	v_add_f32_e32 v241, s46, v241
	v_add_f32_e32 v247, s50, v247
	v_add_f32_e32 v169, s39, v169
	v_add_f32_e32 v175, s43, v175
	v_add_f32_e32 v242, s47, v242
	v_add_f32_e32 v248, s51, v248
	v_add_f32_e32 v168, v168, v169
	v_add_f32_e32 v174, v174, v175
	v_add_f32_e32 v241, v241, v242
	v_add_f32_e32 v247, v247, v248
	v_fmamk_f32 v100, v168, 0xbc800000, v100
	v_fmamk_f32 v105, v174, 0xbc800000, v105
	v_fmamk_f32 v110, v241, 0xbc800000, v110
	v_fmamk_f32 v115, v247, 0xbc800000, v115
	v_mul_f32_e32 v168, v100, v100
	v_mul_f32_e32 v174, v105, v105
	v_mul_f32_e32 v241, v110, v110
	v_mul_f32_e32 v247, v115, v115
	v_mov_b32_dpp v168, v168 quad_perm:[1,0,3,2] row_mask:0xf bank_mask:0xf bound_ctrl:1
; __device__ __forceinline__ float dpp_xor1(float x) { return __builtin_bit_cast(float, __builtin_amdgcn_update_dpp(0, __builtin_bit_cast(int, x), 0xB1, 0xF, 0xF, true)); }
; __device__ __forceinline__ float dpp_xor2(float x) { return __builtin_bit_cast(float, __builtin_amdgcn_update_dpp(0, __builtin_bit_cast(int, x), 0x4E, 0xF, 0xF, true)); }
; __device__ __forceinline__ float dpp_hmir(float x) { return __builtin_bit_cast(float, __builtin_amdgcn_update_dpp(0, __builtin_bit_cast(int, x), 0x141, 0xF, 0xF, true)); }
; __device__ __forceinline__ float dpp_mir(float x)  { return __builtin_bit_cast(float, __builtin_amdgcn_update_dpp(0, __builtin_bit_cast(int, x), 0x140, 0xF, 0xF, true)); }
; __device__ __forceinline__ float red16(float x) { x += dpp_xor1(x); x += dpp_xor2(x); x += dpp_hmir(x); x += dpp_mir(x); return x; }
; __device__ __forceinline__ float wsum(float x) {
;     x = red16(x); const int xi = __builtin_bit_cast(int, x);
;     const float r0 = __builtin_bit_cast(float, __builtin_amdgcn_readlane(xi, 0)), r1 = __builtin_bit_cast(float, __builtin_amdgcn_readlane(xi, 16));
;     const float r2 = __builtin_bit_cast(float, __builtin_amdgcn_readlane(xi, 32)), r3 = __builtin_bit_cast(float, __builtin_amdgcn_readlane(xi, 48));
;     return (r0 + r1) + (r2 + r3);
; __device__ __forceinline__ void rw_post(Frame& F) {
;     ...
;             for (int q = 0; q < 8; ++q) { const int row = rb0 + t0 + q;
;                 const float mean = wsum(y[q]) * (1.f / 64.f); const float dv = y[q] - mean; const float var = wsum(dv * dv) * (1.f / 64.f);
;                 const float yn = dv * (1.f / sqrtf(var + 64e-5f)) * g_ + b_;
	v_mov_b32_dpp v174, v174 quad_perm:[1,0,3,2] row_mask:0xf bank_mask:0xf bound_ctrl:1
	v_mov_b32_dpp v241, v241 quad_perm:[1,0,3,2] row_mask:0xf bank_mask:0xf bound_ctrl:1
	v_mov_b32_dpp v247, v247 quad_perm:[1,0,3,2] row_mask:0xf bank_mask:0xf bound_ctrl:1
	v_fmac_f32_e32 v168, v100, v100
	v_fmac_f32_e32 v174, v105, v105
	v_fmac_f32_e32 v241, v110, v110
	v_fmac_f32_e32 v247, v115, v115
	v_add_f32_dpp v168, v168, v168 quad_perm:[2,3,0,1] row_mask:0xf bank_mask:0xf bound_ctrl:1
	v_add_f32_dpp v174, v174, v174 quad_perm:[2,3,0,1] row_mask:0xf bank_mask:0xf bound_ctrl:1
	v_add_f32_dpp v241, v241, v241 quad_perm:[2,3,0,1] row_mask:0xf bank_mask:0xf bound_ctrl:1
	v_add_f32_dpp v247, v247, v247 quad_perm:[2,3,0,1] row_mask:0xf bank_mask:0xf bound_ctrl:1
	v_add_f32_dpp v168, v168, v168 row_half_mirror row_mask:0xf bank_mask:0xf bound_ctrl:1
	v_add_f32_dpp v174, v174, v174 row_half_mirror row_mask:0xf bank_mask:0xf bound_ctrl:1
	v_add_f32_dpp v241, v241, v241 row_half_mirror row_mask:0xf bank_mask:0xf bound_ctrl:1
	v_add_f32_dpp v247, v247, v247 row_half_mirror row_mask:0xf bank_mask:0xf bound_ctrl:1
	v_add_f32_dpp v168, v168, v168 row_mirror row_mask:0xf bank_mask:0xf bound_ctrl:1
	v_add_f32_dpp v174, v174, v174 row_mirror row_mask:0xf bank_mask:0xf bound_ctrl:1
	v_add_f32_dpp v241, v241, v241 row_mirror row_mask:0xf bank_mask:0xf bound_ctrl:1
	v_add_f32_dpp v247, v247, v247 row_mirror row_mask:0xf bank_mask:0xf bound_ctrl:1
	v_readlane_b32 s36, v168, 16
	v_readlane_b32 s40, v174, 16
	v_readlane_b32 s44, v241, 16
	v_readlane_b32 s48, v247, 16
	v_readlane_b32 s37, v168, 48
	v_readlane_b32 s41, v174, 48
	v_readlane_b32 s45, v241, 48
	v_readlane_b32 s49, v247, 48
	v_readlane_b32 s38, v168, 0
	v_readlane_b32 s42, v174, 0
	v_readlane_b32 s46, v241, 0
	v_readlane_b32 s50, v247, 0
	v_readlane_b32 s39, v168, 32
	v_readlane_b32 s43, v174, 32
	v_readlane_b32 s47, v241, 32
	v_readlane_b32 s51, v247, 32
	v_mov_b32_e32 v168, s36
	v_mov_b32_e32 v174, s40
	v_mov_b32_e32 v241, s44
	v_mov_b32_e32 v247, s48
	v_mov_b32_e32 v169, s37
	v_mov_b32_e32 v175, s41
	v_mov_b32_e32 v242, s45
	v_mov_b32_e32 v248, s49
	v_add_f32_e32 v168, s38, v168
	v_add_f32_e32 v174, s42, v174
	v_add_f32_e32 v241, s46, v241
	v_add_f32_e32 v247, s50, v247
	v_add_f32_e32 v169, s39, v169
	v_add_f32_e32 v175, s43, v175
	v_add_f32_e32 v242, s47, v242
	v_add_f32_e32 v248, s51, v248
	v_add_f32_e32 v168, v168, v169
	v_add_f32_e32 v174, v174, v175
	v_add_f32_e32 v241, v241, v242
	v_add_f32_e32 v247, v247, v248
	v_fmamk_f32 v168, v168, 0x3c800000, v9
	v_fmamk_f32 v174, v174, 0x3c800000, v9
	v_fmamk_f32 v241, v241, 0x3c800000, v9
	v_fmamk_f32 v247, v247, 0x3c800000, v9
	v_mul_f32_e32 v169, 0x4f800000, v168
	v_mul_f32_e32 v175, 0x4f800000, v174
	v_mul_f32_e32 v242, 0x4f800000, v241
	v_mul_f32_e32 v248, 0x4f800000, v247
	v_cmp_gt_f32_e64 s[52:53], s68, v168
	v_cmp_gt_f32_e64 s[54:55], s68, v174
	v_cmp_gt_f32_e64 s[56:57], s68, v241
	v_cmp_gt_f32_e64 s[58:59], s68, v247
	v_mov_b32_e32 v170, v168
	v_mov_b32_e32 v176, v174
	v_mov_b32_e32 v243, v241
	v_mov_b32_e32 v249, v247
	v_cndmask_b32_e64 v168, v170, v169, s[52:53]
	v_cndmask_b32_e64 v174, v176, v175, s[54:55]
	v_cndmask_b32_e64 v241, v243, v242, s[56:57]
	v_cndmask_b32_e64 v247, v249, v248, s[58:59]
	v_sqrt_f32_e32 v169, v168
	v_sqrt_f32_e32 v175, v174
	v_sqrt_f32_e32 v242, v241
	v_sqrt_f32_e32 v248, v247
	v_add_u32_e32 v170, -1, v169
	v_add_u32_e32 v176, -1, v175
	v_add_u32_e32 v243, -1, v242
	v_add_u32_e32 v249, -1, v248
	v_fma_f32 v171, -v170, v169, v168
	v_fma_f32 v177, -v176, v175, v174
	v_fma_f32 v244, -v243, v242, v241
	v_fma_f32 v250, -v249, v248, v247
	v_cmp_ge_f32_e64 s[60:61], 0, v171
	v_cmp_ge_f32_e64 s[62:63], 0, v177
	v_cmp_ge_f32_e64 s[64:65], 0, v244
	v_cmp_ge_f32_e64 s[66:67], 0, v250
	v_add_u32_e32 v171, 1, v169
	v_add_u32_e32 v177, 1, v175
	v_add_u32_e32 v244, 1, v242
	v_add_u32_e32 v250, 1, v248
	v_cndmask_b32_e64 v170, v169, v170, s[60:61]
	v_cndmask_b32_e64 v176, v175, v176, s[62:63]
	v_cndmask_b32_e64 v243, v242, v243, s[64:65]
	v_cndmask_b32_e64 v249, v248, v249, s[66:67]
	v_fma_f32 v169, -v171, v169, v168
	v_fma_f32 v175, -v177, v175, v174
	v_fma_f32 v242, -v244, v242, v241
	v_fma_f32 v248, -v250, v248, v247
	v_cmp_lt_f32_e64 s[60:61], 0, v169
	v_cmp_lt_f32_e64 s[62:63], 0, v175
	v_cmp_lt_f32_e64 s[64:65], 0, v242
	v_cmp_lt_f32_e64 s[66:67], 0, v248
	v_cndmask_b32_e64 v169, v170, v171, s[60:61]
	v_cndmask_b32_e64 v175, v176, v177, s[62:63]
	v_cndmask_b32_e64 v242, v243, v244, s[64:65]
	v_cndmask_b32_e64 v248, v249, v250, s[66:67]
	v_mul_f32_e32 v170, 0x37800000, v169
	v_mul_f32_e32 v176, 0x37800000, v175
	v_mul_f32_e32 v243, 0x37800000, v242
	v_mul_f32_e32 v249, 0x37800000, v248
	v_cndmask_b32_e64 v169, v169, v170, s[52:53]
	v_cndmask_b32_e64 v175, v175, v176, s[54:55]
	v_cndmask_b32_e64 v242, v242, v243, s[56:57]
	v_cndmask_b32_e64 v248, v248, v249, s[58:59]
	v_cmp_class_f32_e64 s[60:61], v168, v8
	v_cmp_class_f32_e64 s[62:63], v174, v8
	v_cmp_class_f32_e64 s[64:65], v241, v8
	v_cmp_class_f32_e64 s[66:67], v247, v8
	v_cndmask_b32_e64 v168, v169, v168, s[60:61]
	v_cndmask_b32_e64 v174, v175, v174, s[62:63]
	v_cndmask_b32_e64 v241, v242, v241, s[64:65]
	v_cndmask_b32_e64 v247, v248, v247, s[66:67]
	v_div_scale_f32 v169, s[60:61], v168, v168, 1.0
	v_rcp_f32_e32 v170, v169
	s_nop 0
	v_fma_f32 v171, -v169, v170, 1.0
	v_fmac_f32_e32 v170, v171, v170
	v_div_scale_f32 v171, vcc, 1.0, v168, 1.0
	v_mul_f32_e32 v172, v171, v170
	v_fma_f32 v173, -v169, v172, v171
	v_fmac_f32_e32 v172, v173, v170
	v_fma_f32 v169, -v169, v172, v171
	v_div_fmas_f32 v169, v169, v170, v172
	v_div_fixup_f32 v168, v169, v168, 1.0
	v_div_scale_f32 v175, s[62:63], v174, v174, 1.0
; #define LAS __attribute__((address_space(3)))
; __device__ __forceinline__ float bf2f(bf16 x) { return __uint_as_float(((unsigned)x) << 16); }
; __device__ __forceinline__ unsigned f2bf(float f) { return cvt_pk_bf16(f, 0.f) & 0xffffu; }
; __device__ __forceinline__ void rw_post(Frame& F) {
;     ...
;             if (k > 0) {
;                 LAS float* cs = (LAS float*)(F.lds + 131072 + F.wave * 1024);
; #pragma unroll
;                 for (int hf = 0; hf < 2; ++hf) {
; #pragma unroll
;                     for (int q = 0; q < 4; ++q) cs[q * 64 + lane] = cc[4 * hf + q];
;                     asm volatile("s_waitcnt lgkmcnt(0)" ::: "memory");
; #pragma unroll
;                     for (int q = 0; q < 4; ++q) { f32x4 a = (f32x4){0.f, 0.f, 0.f, 0.f};
; #pragma unroll
;                         for (int i = 0; i < 16; ++i) a = __builtin_elementwise_fma(Sr[i], *(const LAS f32x4*)(cs + q * 64 + 4 * i), a);
;                         y[4 * hf + q] += (a[0] + a[1]) + (a[2] + a[3]); }
;                     asm volatile("s_waitcnt lgkmcnt(0)" ::: "memory"); }
;             }
; #pragma unroll
;             for (int q = 0; q < 8; ++q) { const int row = rb0 + t0 + q;
;                 const float mean = wsum(y[q]) * (1.f / 64.f); const float dv = y[q] - mean; const float var = wsum(dv * dv) * (1.f / 64.f);
;                 const float yn = dv * (1.f / sqrtf(var + 64e-5f)) * g_ + b_;
;                 OB[(size_t)row * DH + col] = (bf16)f2bf((yn + rk[q] * vv[q]) * bf2f(gg[q])); }
	v_rcp_f32_e32 v176, v175
	s_nop 0
	v_fma_f32 v177, -v175, v176, 1.0
	v_fmac_f32_e32 v176, v177, v176
	v_div_scale_f32 v177, vcc, 1.0, v174, 1.0
	v_mul_f32_e32 v236, v177, v176
	v_fma_f32 v237, -v175, v236, v177
	v_fmac_f32_e32 v236, v237, v176
	v_fma_f32 v175, -v175, v236, v177
	v_div_fmas_f32 v175, v175, v176, v236
	v_div_fixup_f32 v174, v175, v174, 1.0
	v_div_scale_f32 v242, s[64:65], v241, v241, 1.0
	v_rcp_f32_e32 v243, v242
	s_nop 0
	v_fma_f32 v244, -v242, v243, 1.0
	v_fmac_f32_e32 v243, v244, v243
	v_div_scale_f32 v244, vcc, 1.0, v241, 1.0
	v_mul_f32_e32 v245, v244, v243
	v_fma_f32 v246, -v242, v245, v244
	v_fmac_f32_e32 v245, v246, v243
	v_fma_f32 v242, -v242, v245, v244
	v_div_fmas_f32 v242, v242, v243, v245
	v_div_fixup_f32 v241, v242, v241, 1.0
	v_div_scale_f32 v248, s[66:67], v247, v247, 1.0
	v_rcp_f32_e32 v249, v248
	s_nop 0
	v_fma_f32 v250, -v248, v249, 1.0
	v_fmac_f32_e32 v249, v250, v249
	v_div_scale_f32 v250, vcc, 1.0, v247, 1.0
	v_mul_f32_e32 v251, v250, v249
	v_fma_f32 v252, -v248, v251, v250
	v_fmac_f32_e32 v251, v252, v249
	v_fma_f32 v248, -v248, v251, v250
	v_div_fmas_f32 v248, v248, v249, v251
	v_div_fixup_f32 v247, v248, v247, 1.0
	v_mul_f32_e32 v100, v100, v168
	v_mul_f32_e32 v105, v105, v174
	v_mul_f32_e32 v110, v110, v241
	v_mul_f32_e32 v115, v115, v247
	v_lshlrev_b32_e32 v103, 16, v103
	v_lshlrev_b32_e32 v108, 16, v108
	v_lshlrev_b32_e32 v113, 16, v113
	v_lshlrev_b32_e32 v118, 16, v118
	v_fma_f32 v100, v6, v100, v7
	v_fma_f32 v105, v6, v105, v7
	v_fma_f32 v110, v6, v110, v7
	v_fma_f32 v115, v6, v115, v7
	v_fmac_f32_e32 v100, v104, v101
	v_fmac_f32_e32 v105, v109, v106
	v_fmac_f32_e32 v110, v114, v111
	v_fmac_f32_e32 v115, v119, v116
	v_mul_f32_e32 v100, v100, v103
	v_mul_f32_e32 v105, v105, v108
	v_mul_f32_e32 v110, v110, v113
	v_mul_f32_e32 v115, v115, v118
	v_cvt_pk_bf16_f32 v169, v100, v100
	v_cvt_pk_bf16_f32 v175, v105, v105
	v_cvt_pk_bf16_f32 v242, v110, v110
	v_cvt_pk_bf16_f32 v248, v115, v115
	global_store_short v2, v169, s[28:29]
	s_add_u32 s28, s28, 0x1000
	s_addc_u32 s29, s29, 0
	global_store_short v2, v175, s[28:29]
	s_add_u32 s28, s28, 0x1000
	s_addc_u32 s29, s29, 0
	global_store_short v2, v242, s[28:29]
	s_add_u32 s28, s28, 0x1000
	s_addc_u32 s29, s29, 0
	global_store_short v2, v248, s[28:29]
	s_add_u32 s28, s28, 0x1000
	s_addc_u32 s29, s29, 0
	s_waitcnt vmcnt(4)
	s_cmp_eq_u32 s23, 0
	s_cbranch_scc1 .Lpo_nc3
	ds_write_b32 v3, v122
	ds_write_b32 v3, v127 offset:256
	ds_write_b32 v3, v132 offset:512
	ds_write_b32 v3, v137 offset:768
	s_waitcnt lgkmcnt(0)
	ds_read_b128 v[204:207], v4 offset:0
	ds_read_b128 v[208:211], v4 offset:256
	ds_read_b128 v[212:215], v4 offset:512
	ds_read_b128 v[216:219], v4 offset:768
	ds_read_b128 v[220:223], v4 offset:16
	ds_read_b128 v[224:227], v4 offset:272
	ds_read_b128 v[228:231], v4 offset:528
	ds_read_b128 v[232:235], v4 offset:784
	s_waitcnt lgkmcnt(4)
	v_pk_mul_f32 v[184:185], v[16:17], v[204:205]
	v_pk_mul_f32 v[188:189], v[16:17], v[208:209]
	v_pk_mul_f32 v[192:193], v[16:17], v[212:213]
	v_pk_mul_f32 v[196:197], v[16:17], v[216:217]
	v_pk_mul_f32 v[186:187], v[18:19], v[206:207]
	v_pk_mul_f32 v[190:191], v[18:19], v[210:211]
	v_pk_mul_f32 v[194:195], v[18:19], v[214:215]
	v_pk_mul_f32 v[198:199], v[18:19], v[218:219]
	ds_read_b128 v[204:207], v4 offset:32
	ds_read_b128 v[208:211], v4 offset:288
	ds_read_b128 v[212:215], v4 offset:544
	ds_read_b128 v[216:219], v4 offset:800
	s_waitcnt lgkmcnt(4)
	v_pk_fma_f32 v[184:185], v[20:21], v[220:221], v[184:185]
	v_pk_fma_f32 v[188:189], v[20:21], v[224:225], v[188:189]
	v_pk_fma_f32 v[192:193], v[20:21], v[228:229], v[192:193]
	v_pk_fma_f32 v[196:197], v[20:21], v[232:233], v[196:197]
	v_pk_fma_f32 v[186:187], v[22:23], v[222:223], v[186:187]
	v_pk_fma_f32 v[190:191], v[22:23], v[226:227], v[190:191]
	v_pk_fma_f32 v[194:195], v[22:23], v[230:231], v[194:195]
	v_pk_fma_f32 v[198:199], v[22:23], v[234:235], v[198:199]
	ds_read_b128 v[220:223], v4 offset:48
	ds_read_b128 v[224:227], v4 offset:304
	ds_read_b128 v[228:231], v4 offset:560
	ds_read_b128 v[232:235], v4 offset:816
	s_waitcnt lgkmcnt(4)
	v_pk_fma_f32 v[184:185], v[24:25], v[204:205], v[184:185]
	v_pk_fma_f32 v[188:189], v[24:25], v[208:209], v[188:189]
	v_pk_fma_f32 v[192:193], v[24:25], v[212:213], v[192:193]
	v_pk_fma_f32 v[196:197], v[24:25], v[216:217], v[196:197]
	v_pk_fma_f32 v[186:187], v[26:27], v[206:207], v[186:187]
	v_pk_fma_f32 v[190:191], v[26:27], v[210:211], v[190:191]
	v_pk_fma_f32 v[194:195], v[26:27], v[214:215], v[194:195]
	v_pk_fma_f32 v[198:199], v[26:27], v[218:219], v[198:199]
	ds_read_b128 v[204:207], v4 offset:64
	ds_read_b128 v[208:211], v4 offset:320
	ds_read_b128 v[212:215], v4 offset:576
	ds_read_b128 v[216:219], v4 offset:832
	s_waitcnt lgkmcnt(4)
	v_pk_fma_f32 v[184:185], v[28:29], v[220:221], v[184:185]
	v_pk_fma_f32 v[188:189], v[28:29], v[224:225], v[188:189]
	v_pk_fma_f32 v[192:193], v[28:29], v[228:229], v[192:193]
	v_pk_fma_f32 v[196:197], v[28:29], v[232:233], v[196:197]
	v_pk_fma_f32 v[186:187], v[30:31], v[222:223], v[186:187]
	v_pk_fma_f32 v[190:191], v[30:31], v[226:227], v[190:191]
	v_pk_fma_f32 v[194:195], v[30:31], v[230:231], v[194:195]
	v_pk_fma_f32 v[198:199], v[30:31], v[234:235], v[198:199]
	ds_read_b128 v[220:223], v4 offset:80
	ds_read_b128 v[224:227], v4 offset:336
	ds_read_b128 v[228:231], v4 offset:592
	ds_read_b128 v[232:235], v4 offset:848
	s_waitcnt lgkmcnt(4)
; #define LAS __attribute__((address_space(3)))
; __device__ __forceinline__ void rw_post(Frame& F) {
;     ...
;                 for (int hf = 0; hf < 2; ++hf) {
; #pragma unroll
;                     for (int q = 0; q < 4; ++q) cs[q * 64 + lane] = cc[4 * hf + q];
;                     asm volatile("s_waitcnt lgkmcnt(0)" ::: "memory");
; #pragma unroll
;                     for (int q = 0; q < 4; ++q) { f32x4 a = (f32x4){0.f, 0.f, 0.f, 0.f};
; #pragma unroll
;                         for (int i = 0; i < 16; ++i) a = __builtin_elementwise_fma(Sr[i], *(const LAS f32x4*)(cs + q * 64 + 4 * i), a);
;                         y[4 * hf + q] += (a[0] + a[1]) + (a[2] + a[3]); }
;                     asm volatile("s_waitcnt lgkmcnt(0)" ::: "memory"); }
	v_pk_fma_f32 v[184:185], v[32:33], v[204:205], v[184:185]
	v_pk_fma_f32 v[188:189], v[32:33], v[208:209], v[188:189]
	v_pk_fma_f32 v[192:193], v[32:33], v[212:213], v[192:193]
	v_pk_fma_f32 v[196:197], v[32:33], v[216:217], v[196:197]
	v_pk_fma_f32 v[186:187], v[34:35], v[206:207], v[186:187]
	v_pk_fma_f32 v[190:191], v[34:35], v[210:211], v[190:191]
	v_pk_fma_f32 v[194:195], v[34:35], v[214:215], v[194:195]
	v_pk_fma_f32 v[198:199], v[34:35], v[218:219], v[198:199]
	ds_read_b128 v[204:207], v4 offset:96
	ds_read_b128 v[208:211], v4 offset:352
	ds_read_b128 v[212:215], v4 offset:608
	ds_read_b128 v[216:219], v4 offset:864
	s_waitcnt lgkmcnt(4)
	v_pk_fma_f32 v[184:185], v[36:37], v[220:221], v[184:185]
	v_pk_fma_f32 v[188:189], v[36:37], v[224:225], v[188:189]
	v_pk_fma_f32 v[192:193], v[36:37], v[228:229], v[192:193]
	v_pk_fma_f32 v[196:197], v[36:37], v[232:233], v[196:197]
	v_pk_fma_f32 v[186:187], v[38:39], v[222:223], v[186:187]
	v_pk_fma_f32 v[190:191], v[38:39], v[226:227], v[190:191]
	v_pk_fma_f32 v[194:195], v[38:39], v[230:231], v[194:195]
	v_pk_fma_f32 v[198:199], v[38:39], v[234:235], v[198:199]
	ds_read_b128 v[220:223], v4 offset:112
	ds_read_b128 v[224:227], v4 offset:368
	ds_read_b128 v[228:231], v4 offset:624
	ds_read_b128 v[232:235], v4 offset:880
	s_waitcnt lgkmcnt(4)
	v_pk_fma_f32 v[184:185], v[40:41], v[204:205], v[184:185]
	v_pk_fma_f32 v[188:189], v[40:41], v[208:209], v[188:189]
	v_pk_fma_f32 v[192:193], v[40:41], v[212:213], v[192:193]
	v_pk_fma_f32 v[196:197], v[40:41], v[216:217], v[196:197]
	v_pk_fma_f32 v[186:187], v[42:43], v[206:207], v[186:187]
	v_pk_fma_f32 v[190:191], v[42:43], v[210:211], v[190:191]
	v_pk_fma_f32 v[194:195], v[42:43], v[214:215], v[194:195]
	v_pk_fma_f32 v[198:199], v[42:43], v[218:219], v[198:199]
	ds_read_b128 v[204:207], v4 offset:128
	ds_read_b128 v[208:211], v4 offset:384
	ds_read_b128 v[212:215], v4 offset:640
	ds_read_b128 v[216:219], v4 offset:896
	s_waitcnt lgkmcnt(4)
	v_pk_fma_f32 v[184:185], v[44:45], v[220:221], v[184:185]
	v_pk_fma_f32 v[188:189], v[44:45], v[224:225], v[188:189]
	v_pk_fma_f32 v[192:193], v[44:45], v[228:229], v[192:193]
	v_pk_fma_f32 v[196:197], v[44:45], v[232:233], v[196:197]
	v_pk_fma_f32 v[186:187], v[46:47], v[222:223], v[186:187]
	v_pk_fma_f32 v[190:191], v[46:47], v[226:227], v[190:191]
	v_pk_fma_f32 v[194:195], v[46:47], v[230:231], v[194:195]
	v_pk_fma_f32 v[198:199], v[46:47], v[234:235], v[198:199]
	ds_read_b128 v[220:223], v4 offset:144
	ds_read_b128 v[224:227], v4 offset:400
	ds_read_b128 v[228:231], v4 offset:656
	ds_read_b128 v[232:235], v4 offset:912
	s_waitcnt lgkmcnt(4)
	v_pk_fma_f32 v[184:185], v[48:49], v[204:205], v[184:185]
	v_pk_fma_f32 v[188:189], v[48:49], v[208:209], v[188:189]
	v_pk_fma_f32 v[192:193], v[48:49], v[212:213], v[192:193]
	v_pk_fma_f32 v[196:197], v[48:49], v[216:217], v[196:197]
	v_pk_fma_f32 v[186:187], v[50:51], v[206:207], v[186:187]
	v_pk_fma_f32 v[190:191], v[50:51], v[210:211], v[190:191]
	v_pk_fma_f32 v[194:195], v[50:51], v[214:215], v[194:195]
	v_pk_fma_f32 v[198:199], v[50:51], v[218:219], v[198:199]
	ds_read_b128 v[204:207], v4 offset:160
	ds_read_b128 v[208:211], v4 offset:416
	ds_read_b128 v[212:215], v4 offset:672
	ds_read_b128 v[216:219], v4 offset:928
	s_waitcnt lgkmcnt(4)
	v_pk_fma_f32 v[184:185], v[52:53], v[220:221], v[184:185]
	v_pk_fma_f32 v[188:189], v[52:53], v[224:225], v[188:189]
	v_pk_fma_f32 v[192:193], v[52:53], v[228:229], v[192:193]
	v_pk_fma_f32 v[196:197], v[52:53], v[232:233], v[196:197]
	v_pk_fma_f32 v[186:187], v[54:55], v[222:223], v[186:187]
	v_pk_fma_f32 v[190:191], v[54:55], v[226:227], v[190:191]
	v_pk_fma_f32 v[194:195], v[54:55], v[230:231], v[194:195]
	v_pk_fma_f32 v[198:199], v[54:55], v[234:235], v[198:199]
	ds_read_b128 v[220:223], v4 offset:176
	ds_read_b128 v[224:227], v4 offset:432
	ds_read_b128 v[228:231], v4 offset:688
	ds_read_b128 v[232:235], v4 offset:944
	s_waitcnt lgkmcnt(4)
	v_pk_fma_f32 v[184:185], v[56:57], v[204:205], v[184:185]
	v_pk_fma_f32 v[188:189], v[56:57], v[208:209], v[188:189]
	v_pk_fma_f32 v[192:193], v[56:57], v[212:213], v[192:193]
	v_pk_fma_f32 v[196:197], v[56:57], v[216:217], v[196:197]
	v_pk_fma_f32 v[186:187], v[58:59], v[206:207], v[186:187]
	v_pk_fma_f32 v[190:191], v[58:59], v[210:211], v[190:191]
	v_pk_fma_f32 v[194:195], v[58:59], v[214:215], v[194:195]
	v_pk_fma_f32 v[198:199], v[58:59], v[218:219], v[198:199]
	ds_read_b128 v[204:207], v4 offset:192
	ds_read_b128 v[208:211], v4 offset:448
	ds_read_b128 v[212:215], v4 offset:704
	ds_read_b128 v[216:219], v4 offset:960
	s_waitcnt lgkmcnt(4)
	v_pk_fma_f32 v[184:185], v[60:61], v[220:221], v[184:185]
	v_pk_fma_f32 v[188:189], v[60:61], v[224:225], v[188:189]
	v_pk_fma_f32 v[192:193], v[60:61], v[228:229], v[192:193]
	v_pk_fma_f32 v[196:197], v[60:61], v[232:233], v[196:197]
	v_pk_fma_f32 v[186:187], v[62:63], v[222:223], v[186:187]
	v_pk_fma_f32 v[190:191], v[62:63], v[226:227], v[190:191]
	v_pk_fma_f32 v[194:195], v[62:63], v[230:231], v[194:195]
	v_pk_fma_f32 v[198:199], v[62:63], v[234:235], v[198:199]
	ds_read_b128 v[220:223], v4 offset:208
	ds_read_b128 v[224:227], v4 offset:464
	ds_read_b128 v[228:231], v4 offset:720
	ds_read_b128 v[232:235], v4 offset:976
	s_waitcnt lgkmcnt(4)
	v_pk_fma_f32 v[184:185], v[64:65], v[204:205], v[184:185]
	v_pk_fma_f32 v[188:189], v[64:65], v[208:209], v[188:189]
	v_pk_fma_f32 v[192:193], v[64:65], v[212:213], v[192:193]
	v_pk_fma_f32 v[196:197], v[64:65], v[216:217], v[196:197]
	v_pk_fma_f32 v[186:187], v[66:67], v[206:207], v[186:187]
	v_pk_fma_f32 v[190:191], v[66:67], v[210:211], v[190:191]
	v_pk_fma_f32 v[194:195], v[66:67], v[214:215], v[194:195]
	v_pk_fma_f32 v[198:199], v[66:67], v[218:219], v[198:199]
	ds_read_b128 v[204:207], v4 offset:224
	ds_read_b128 v[208:211], v4 offset:480
	ds_read_b128 v[212:215], v4 offset:736
	ds_read_b128 v[216:219], v4 offset:992
	s_waitcnt lgkmcnt(4)
; #define LAS __attribute__((address_space(3)))
; __device__ __forceinline__ void rw_post(Frame& F) {
;     ...
;                     for (int q = 0; q < 4; ++q) { f32x4 a = (f32x4){0.f, 0.f, 0.f, 0.f};
; #pragma unroll
;                         for (int i = 0; i < 16; ++i) a = __builtin_elementwise_fma(Sr[i], *(const LAS f32x4*)(cs + q * 64 + 4 * i), a);
;                         y[4 * hf + q] += (a[0] + a[1]) + (a[2] + a[3]); }
;                     asm volatile("s_waitcnt lgkmcnt(0)" ::: "memory"); }
;             }
; #pragma unroll
;             for (int q = 0; q < 8; ++q) { const int row = rb0 + t0 + q;
;                 const float mean = wsum(y[q]) * (1.f / 64.f); const float dv = y[q] - mean; const float var = wsum(dv * dv) * (1.f / 64.f);
	v_pk_fma_f32 v[184:185], v[68:69], v[220:221], v[184:185]
	v_pk_fma_f32 v[188:189], v[68:69], v[224:225], v[188:189]
	v_pk_fma_f32 v[192:193], v[68:69], v[228:229], v[192:193]
	v_pk_fma_f32 v[196:197], v[68:69], v[232:233], v[196:197]
	v_pk_fma_f32 v[186:187], v[70:71], v[222:223], v[186:187]
	v_pk_fma_f32 v[190:191], v[70:71], v[226:227], v[190:191]
	v_pk_fma_f32 v[194:195], v[70:71], v[230:231], v[194:195]
	v_pk_fma_f32 v[198:199], v[70:71], v[234:235], v[198:199]
	ds_read_b128 v[220:223], v4 offset:240
	ds_read_b128 v[224:227], v4 offset:496
	ds_read_b128 v[228:231], v4 offset:752
	ds_read_b128 v[232:235], v4 offset:1008
	s_waitcnt lgkmcnt(4)
	v_pk_fma_f32 v[184:185], v[72:73], v[204:205], v[184:185]
	v_pk_fma_f32 v[188:189], v[72:73], v[208:209], v[188:189]
	v_pk_fma_f32 v[192:193], v[72:73], v[212:213], v[192:193]
	v_pk_fma_f32 v[196:197], v[72:73], v[216:217], v[196:197]
	v_pk_fma_f32 v[186:187], v[74:75], v[206:207], v[186:187]
	v_pk_fma_f32 v[190:191], v[74:75], v[210:211], v[190:191]
	v_pk_fma_f32 v[194:195], v[74:75], v[214:215], v[194:195]
	v_pk_fma_f32 v[198:199], v[74:75], v[218:219], v[198:199]
	s_waitcnt lgkmcnt(0)
	v_pk_fma_f32 v[184:185], v[76:77], v[220:221], v[184:185]
	v_pk_fma_f32 v[188:189], v[76:77], v[224:225], v[188:189]
	v_pk_fma_f32 v[192:193], v[76:77], v[228:229], v[192:193]
	v_pk_fma_f32 v[196:197], v[76:77], v[232:233], v[196:197]
	v_pk_fma_f32 v[186:187], v[78:79], v[222:223], v[186:187]
	v_pk_fma_f32 v[190:191], v[78:79], v[226:227], v[190:191]
	v_pk_fma_f32 v[194:195], v[78:79], v[230:231], v[194:195]
	v_pk_fma_f32 v[198:199], v[78:79], v[234:235], v[198:199]
	v_add_f32_e32 v184, v184, v185
	v_add_f32_e32 v188, v188, v189
	v_add_f32_e32 v192, v192, v193
	v_add_f32_e32 v196, v196, v197
	v_add_f32_e32 v186, v186, v187
	v_add_f32_e32 v190, v190, v191
	v_add_f32_e32 v194, v194, v195
	v_add_f32_e32 v198, v198, v199
	v_add_f32_e32 v184, v184, v186
	v_add_f32_e32 v188, v188, v190
	v_add_f32_e32 v192, v192, v194
	v_add_f32_e32 v196, v196, v198
	v_add_f32_e32 v120, v120, v184
	v_add_f32_e32 v125, v125, v188
	v_add_f32_e32 v130, v130, v192
	v_add_f32_e32 v135, v135, v196
.Lpo_nc3:
	v_add_f32_dpp v168, v120, v120 quad_perm:[1,0,3,2] row_mask:0xf bank_mask:0xf bound_ctrl:1
	v_add_f32_dpp v174, v125, v125 quad_perm:[1,0,3,2] row_mask:0xf bank_mask:0xf bound_ctrl:1
	v_add_f32_dpp v241, v130, v130 quad_perm:[1,0,3,2] row_mask:0xf bank_mask:0xf bound_ctrl:1
	v_add_f32_dpp v247, v135, v135 quad_perm:[1,0,3,2] row_mask:0xf bank_mask:0xf bound_ctrl:1
	v_add_f32_dpp v168, v168, v168 quad_perm:[2,3,0,1] row_mask:0xf bank_mask:0xf bound_ctrl:1
	v_add_f32_dpp v174, v174, v174 quad_perm:[2,3,0,1] row_mask:0xf bank_mask:0xf bound_ctrl:1
	v_add_f32_dpp v241, v241, v241 quad_perm:[2,3,0,1] row_mask:0xf bank_mask:0xf bound_ctrl:1
	v_add_f32_dpp v247, v247, v247 quad_perm:[2,3,0,1] row_mask:0xf bank_mask:0xf bound_ctrl:1
	v_add_f32_dpp v168, v168, v168 row_half_mirror row_mask:0xf bank_mask:0xf bound_ctrl:1
	v_add_f32_dpp v174, v174, v174 row_half_mirror row_mask:0xf bank_mask:0xf bound_ctrl:1
	v_add_f32_dpp v241, v241, v241 row_half_mirror row_mask:0xf bank_mask:0xf bound_ctrl:1
	v_add_f32_dpp v247, v247, v247 row_half_mirror row_mask:0xf bank_mask:0xf bound_ctrl:1
	v_add_f32_dpp v168, v168, v168 row_mirror row_mask:0xf bank_mask:0xf bound_ctrl:1
	v_add_f32_dpp v174, v174, v174 row_mirror row_mask:0xf bank_mask:0xf bound_ctrl:1
	v_add_f32_dpp v241, v241, v241 row_mirror row_mask:0xf bank_mask:0xf bound_ctrl:1
	v_add_f32_dpp v247, v247, v247 row_mirror row_mask:0xf bank_mask:0xf bound_ctrl:1
	v_readlane_b32 s36, v168, 16
	v_readlane_b32 s40, v174, 16
	v_readlane_b32 s44, v241, 16
	v_readlane_b32 s48, v247, 16
	v_readlane_b32 s37, v168, 48
	v_readlane_b32 s41, v174, 48
	v_readlane_b32 s45, v241, 48
	v_readlane_b32 s49, v247, 48
	v_readlane_b32 s38, v168, 0
	v_readlane_b32 s42, v174, 0
	v_readlane_b32 s46, v241, 0
	v_readlane_b32 s50, v247, 0
	v_readlane_b32 s39, v168, 32
	v_readlane_b32 s43, v174, 32
	v_readlane_b32 s47, v241, 32
	v_readlane_b32 s51, v247, 32
	v_mov_b32_e32 v168, s36
	v_mov_b32_e32 v174, s40
	v_mov_b32_e32 v241, s44
	v_mov_b32_e32 v247, s48
	v_mov_b32_e32 v169, s37
	v_mov_b32_e32 v175, s41
	v_mov_b32_e32 v242, s45
	v_mov_b32_e32 v248, s49
	v_add_f32_e32 v168, s38, v168
	v_add_f32_e32 v174, s42, v174
	v_add_f32_e32 v241, s46, v241
	v_add_f32_e32 v247, s50, v247
	v_add_f32_e32 v169, s39, v169
	v_add_f32_e32 v175, s43, v175
	v_add_f32_e32 v242, s47, v242
	v_add_f32_e32 v248, s51, v248
	v_add_f32_e32 v168, v168, v169
	v_add_f32_e32 v174, v174, v175
	v_add_f32_e32 v241, v241, v242
	v_add_f32_e32 v247, v247, v248
	v_fmamk_f32 v120, v168, 0xbc800000, v120
	v_fmamk_f32 v125, v174, 0xbc800000, v125
	v_fmamk_f32 v130, v241, 0xbc800000, v130
	v_fmamk_f32 v135, v247, 0xbc800000, v135
	v_mul_f32_e32 v168, v120, v120
	v_mul_f32_e32 v174, v125, v125
	v_mul_f32_e32 v241, v130, v130
	v_mul_f32_e32 v247, v135, v135
	v_mov_b32_dpp v168, v168 quad_perm:[1,0,3,2] row_mask:0xf bank_mask:0xf bound_ctrl:1
	v_mov_b32_dpp v174, v174 quad_perm:[1,0,3,2] row_mask:0xf bank_mask:0xf bound_ctrl:1
	v_mov_b32_dpp v241, v241 quad_perm:[1,0,3,2] row_mask:0xf bank_mask:0xf bound_ctrl:1
	v_mov_b32_dpp v247, v247 quad_perm:[1,0,3,2] row_mask:0xf bank_mask:0xf bound_ctrl:1
	v_fmac_f32_e32 v168, v120, v120
	v_fmac_f32_e32 v174, v125, v125
	v_fmac_f32_e32 v241, v130, v130
	v_fmac_f32_e32 v247, v135, v135
	v_add_f32_dpp v168, v168, v168 quad_perm:[2,3,0,1] row_mask:0xf bank_mask:0xf bound_ctrl:1
	v_add_f32_dpp v174, v174, v174 quad_perm:[2,3,0,1] row_mask:0xf bank_mask:0xf bound_ctrl:1
	v_add_f32_dpp v241, v241, v241 quad_perm:[2,3,0,1] row_mask:0xf bank_mask:0xf bound_ctrl:1
; __device__ __forceinline__ void rw_post(Frame& F) {
;     ...
;                 const float mean = wsum(y[q]) * (1.f / 64.f); const float dv = y[q] - mean; const float var = wsum(dv * dv) * (1.f / 64.f);
;                 const float yn = dv * (1.f / sqrtf(var + 64e-5f)) * g_ + b_;
	v_add_f32_dpp v247, v247, v247 quad_perm:[2,3,0,1] row_mask:0xf bank_mask:0xf bound_ctrl:1
	v_add_f32_dpp v168, v168, v168 row_half_mirror row_mask:0xf bank_mask:0xf bound_ctrl:1
	v_add_f32_dpp v174, v174, v174 row_half_mirror row_mask:0xf bank_mask:0xf bound_ctrl:1
	v_add_f32_dpp v241, v241, v241 row_half_mirror row_mask:0xf bank_mask:0xf bound_ctrl:1
	v_add_f32_dpp v247, v247, v247 row_half_mirror row_mask:0xf bank_mask:0xf bound_ctrl:1
	v_add_f32_dpp v168, v168, v168 row_mirror row_mask:0xf bank_mask:0xf bound_ctrl:1
	v_add_f32_dpp v174, v174, v174 row_mirror row_mask:0xf bank_mask:0xf bound_ctrl:1
	v_add_f32_dpp v241, v241, v241 row_mirror row_mask:0xf bank_mask:0xf bound_ctrl:1
	v_add_f32_dpp v247, v247, v247 row_mirror row_mask:0xf bank_mask:0xf bound_ctrl:1
	v_readlane_b32 s36, v168, 16
	v_readlane_b32 s40, v174, 16
	v_readlane_b32 s44, v241, 16
	v_readlane_b32 s48, v247, 16
	v_readlane_b32 s37, v168, 48
	v_readlane_b32 s41, v174, 48
	v_readlane_b32 s45, v241, 48
	v_readlane_b32 s49, v247, 48
	v_readlane_b32 s38, v168, 0
	v_readlane_b32 s42, v174, 0
	v_readlane_b32 s46, v241, 0
	v_readlane_b32 s50, v247, 0
	v_readlane_b32 s39, v168, 32
	v_readlane_b32 s43, v174, 32
	v_readlane_b32 s47, v241, 32
	v_readlane_b32 s51, v247, 32
	v_mov_b32_e32 v168, s36
	v_mov_b32_e32 v174, s40
	v_mov_b32_e32 v241, s44
	v_mov_b32_e32 v247, s48
	v_mov_b32_e32 v169, s37
	v_mov_b32_e32 v175, s41
	v_mov_b32_e32 v242, s45
	v_mov_b32_e32 v248, s49
	v_add_f32_e32 v168, s38, v168
	v_add_f32_e32 v174, s42, v174
	v_add_f32_e32 v241, s46, v241
	v_add_f32_e32 v247, s50, v247
	v_add_f32_e32 v169, s39, v169
	v_add_f32_e32 v175, s43, v175
	v_add_f32_e32 v242, s47, v242
	v_add_f32_e32 v248, s51, v248
	v_add_f32_e32 v168, v168, v169
	v_add_f32_e32 v174, v174, v175
	v_add_f32_e32 v241, v241, v242
	v_add_f32_e32 v247, v247, v248
	v_fmamk_f32 v168, v168, 0x3c800000, v9
	v_fmamk_f32 v174, v174, 0x3c800000, v9
	v_fmamk_f32 v241, v241, 0x3c800000, v9
	v_fmamk_f32 v247, v247, 0x3c800000, v9
	v_mul_f32_e32 v169, 0x4f800000, v168
	v_mul_f32_e32 v175, 0x4f800000, v174
	v_mul_f32_e32 v242, 0x4f800000, v241
	v_mul_f32_e32 v248, 0x4f800000, v247
	v_cmp_gt_f32_e64 s[52:53], s68, v168
	v_cmp_gt_f32_e64 s[54:55], s68, v174
	v_cmp_gt_f32_e64 s[56:57], s68, v241
	v_cmp_gt_f32_e64 s[58:59], s68, v247
	v_mov_b32_e32 v170, v168
	v_mov_b32_e32 v176, v174
	v_mov_b32_e32 v243, v241
	v_mov_b32_e32 v249, v247
	v_cndmask_b32_e64 v168, v170, v169, s[52:53]
	v_cndmask_b32_e64 v174, v176, v175, s[54:55]
	v_cndmask_b32_e64 v241, v243, v242, s[56:57]
	v_cndmask_b32_e64 v247, v249, v248, s[58:59]
	v_sqrt_f32_e32 v169, v168
	v_sqrt_f32_e32 v175, v174
	v_sqrt_f32_e32 v242, v241
	v_sqrt_f32_e32 v248, v247
	v_add_u32_e32 v170, -1, v169
	v_add_u32_e32 v176, -1, v175
	v_add_u32_e32 v243, -1, v242
	v_add_u32_e32 v249, -1, v248
	v_fma_f32 v171, -v170, v169, v168
	v_fma_f32 v177, -v176, v175, v174
	v_fma_f32 v244, -v243, v242, v241
	v_fma_f32 v250, -v249, v248, v247
	v_cmp_ge_f32_e64 s[60:61], 0, v171
	v_cmp_ge_f32_e64 s[62:63], 0, v177
	v_cmp_ge_f32_e64 s[64:65], 0, v244
	v_cmp_ge_f32_e64 s[66:67], 0, v250
	v_add_u32_e32 v171, 1, v169
	v_add_u32_e32 v177, 1, v175
	v_add_u32_e32 v244, 1, v242
	v_add_u32_e32 v250, 1, v248
	v_cndmask_b32_e64 v170, v169, v170, s[60:61]
	v_cndmask_b32_e64 v176, v175, v176, s[62:63]
	v_cndmask_b32_e64 v243, v242, v243, s[64:65]
	v_cndmask_b32_e64 v249, v248, v249, s[66:67]
	v_fma_f32 v169, -v171, v169, v168
	v_fma_f32 v175, -v177, v175, v174
	v_fma_f32 v242, -v244, v242, v241
	v_fma_f32 v248, -v250, v248, v247
	v_cmp_lt_f32_e64 s[60:61], 0, v169
	v_cmp_lt_f32_e64 s[62:63], 0, v175
	v_cmp_lt_f32_e64 s[64:65], 0, v242
	v_cmp_lt_f32_e64 s[66:67], 0, v248
	v_cndmask_b32_e64 v169, v170, v171, s[60:61]
	v_cndmask_b32_e64 v175, v176, v177, s[62:63]
	v_cndmask_b32_e64 v242, v243, v244, s[64:65]
	v_cndmask_b32_e64 v248, v249, v250, s[66:67]
	v_mul_f32_e32 v170, 0x37800000, v169
	v_mul_f32_e32 v176, 0x37800000, v175
	v_mul_f32_e32 v243, 0x37800000, v242
	v_mul_f32_e32 v249, 0x37800000, v248
	v_cndmask_b32_e64 v169, v169, v170, s[52:53]
	v_cndmask_b32_e64 v175, v175, v176, s[54:55]
	v_cndmask_b32_e64 v242, v242, v243, s[56:57]
	v_cndmask_b32_e64 v248, v248, v249, s[58:59]
	v_cmp_class_f32_e64 s[60:61], v168, v8
	v_cmp_class_f32_e64 s[62:63], v174, v8
	v_cmp_class_f32_e64 s[64:65], v241, v8
	v_cmp_class_f32_e64 s[66:67], v247, v8
	v_cndmask_b32_e64 v168, v169, v168, s[60:61]
	v_cndmask_b32_e64 v174, v175, v174, s[62:63]
	v_cndmask_b32_e64 v241, v242, v241, s[64:65]
	v_cndmask_b32_e64 v247, v248, v247, s[66:67]
	v_div_scale_f32 v169, s[60:61], v168, v168, 1.0
	v_rcp_f32_e32 v170, v169
	s_nop 0
	v_fma_f32 v171, -v169, v170, 1.0
	v_fmac_f32_e32 v170, v171, v170
	v_div_scale_f32 v171, vcc, 1.0, v168, 1.0
	v_mul_f32_e32 v172, v171, v170
	v_fma_f32 v173, -v169, v172, v171
	v_fmac_f32_e32 v172, v173, v170
	v_fma_f32 v169, -v169, v172, v171
	v_div_fmas_f32 v169, v169, v170, v172
	v_div_fixup_f32 v168, v169, v168, 1.0
	v_div_scale_f32 v175, s[62:63], v174, v174, 1.0
	v_rcp_f32_e32 v176, v175
	s_nop 0
	v_fma_f32 v177, -v175, v176, 1.0
	v_fmac_f32_e32 v176, v177, v176
	v_div_scale_f32 v177, vcc, 1.0, v174, 1.0
	v_mul_f32_e32 v236, v177, v176
	v_fma_f32 v237, -v175, v236, v177
	v_fmac_f32_e32 v236, v237, v176
	v_fma_f32 v175, -v175, v236, v177
	v_div_fmas_f32 v175, v175, v176, v236
	v_div_fixup_f32 v174, v175, v174, 1.0
	v_div_scale_f32 v242, s[64:65], v241, v241, 1.0
	v_rcp_f32_e32 v243, v242
	s_nop 0
	v_fma_f32 v244, -v242, v243, 1.0
	v_fmac_f32_e32 v243, v244, v243
	v_div_scale_f32 v244, vcc, 1.0, v241, 1.0
	v_mul_f32_e32 v245, v244, v243
	v_fma_f32 v246, -v242, v245, v244
	v_fmac_f32_e32 v245, v246, v243
; __device__ __forceinline__ float bf2f(bf16 x) { return __uint_as_float(((unsigned)x) << 16); }
; __device__ __forceinline__ unsigned f2bf(float f) { return cvt_pk_bf16(f, 0.f) & 0xffffu; }
; #define POST_LD(Y_, V_, G_, R_, C_, t) do { _Pragma("unroll") for (int q = 0; q < 8; ++q) { const size_t o_ = (size_t)((t) + q) * DH; Y_[q] = yp[o_]; V_[q] = vp[o_]; G_[q] = gp[o_]; R_[q] = rp[((t) + q) * 32]; C_[q] = cp[o_]; } } while (0)
; __device__ __forceinline__ void rw_post(Frame& F) {
;     ...
;         POST_LD(y, vv, gg, rk, cc, 0);
;         for (int t0 = 0; t0 < 64; t0 += 8) {
;             float ny[8], nv[8], nr[8], nc[8]; bf16 ng[8];
;             const int tn = t0 + 8 < 64 ? t0 + 8 : t0;
;             POST_LD(ny, nv, ng, nr, nc, tn);
;     ...
;             for (int q = 0; q < 8; ++q) { const int row = rb0 + t0 + q;
;                 const float mean = wsum(y[q]) * (1.f / 64.f); const float dv = y[q] - mean; const float var = wsum(dv * dv) * (1.f / 64.f);
;                 const float yn = dv * (1.f / sqrtf(var + 64e-5f)) * g_ + b_;
;                 OB[(size_t)row * DH + col] = (bf16)f2bf((yn + rk[q] * vv[q]) * bf2f(gg[q])); }
	v_fma_f32 v242, -v242, v245, v244
	v_div_fmas_f32 v242, v242, v243, v245
	v_div_fixup_f32 v241, v242, v241, 1.0
	v_div_scale_f32 v248, s[66:67], v247, v247, 1.0
	v_rcp_f32_e32 v249, v248
	s_nop 0
	v_fma_f32 v250, -v248, v249, 1.0
	v_fmac_f32_e32 v249, v250, v249
	v_div_scale_f32 v250, vcc, 1.0, v247, 1.0
	v_mul_f32_e32 v251, v250, v249
	v_fma_f32 v252, -v248, v251, v250
	v_fmac_f32_e32 v251, v252, v249
	v_fma_f32 v248, -v248, v251, v250
	v_div_fmas_f32 v248, v248, v249, v251
	v_div_fixup_f32 v247, v248, v247, 1.0
	v_mul_f32_e32 v120, v120, v168
	v_mul_f32_e32 v125, v125, v174
	v_mul_f32_e32 v130, v130, v241
	v_mul_f32_e32 v135, v135, v247
	v_lshlrev_b32_e32 v123, 16, v123
	v_lshlrev_b32_e32 v128, 16, v128
	v_lshlrev_b32_e32 v133, 16, v133
	v_lshlrev_b32_e32 v138, 16, v138
	v_fma_f32 v120, v6, v120, v7
	v_fma_f32 v125, v6, v125, v7
	v_fma_f32 v130, v6, v130, v7
	v_fma_f32 v135, v6, v135, v7
	v_fmac_f32_e32 v120, v124, v121
	v_fmac_f32_e32 v125, v129, v126
	v_fmac_f32_e32 v130, v134, v131
	v_fmac_f32_e32 v135, v139, v136
	v_mul_f32_e32 v120, v120, v123
	v_mul_f32_e32 v125, v125, v128
	v_mul_f32_e32 v130, v130, v133
	v_mul_f32_e32 v135, v135, v138
	v_cvt_pk_bf16_f32 v169, v120, v120
	v_cvt_pk_bf16_f32 v175, v125, v125
	v_cvt_pk_bf16_f32 v242, v130, v130
	v_cvt_pk_bf16_f32 v248, v135, v135
	global_store_short v2, v169, s[28:29]
	s_add_u32 s28, s28, 0x1000
	s_addc_u32 s29, s29, 0
	global_store_short v2, v175, s[28:29]
	s_add_u32 s28, s28, 0x1000
	s_addc_u32 s29, s29, 0
	global_store_short v2, v242, s[28:29]
	s_add_u32 s28, s28, 0x1000
	s_addc_u32 s29, s29, 0
	global_store_short v2, v248, s[28:29]
	s_add_u32 s28, s28, 0x1000
	s_addc_u32 s29, s29, 0
	s_cmp_eq_u32 s25, 1
	s_cbranch_scc1 .Lpo_nopf
	global_load_dword v80, v1, s[6:7]
	global_load_dword v81, v1, s[8:9]
	global_load_dword v82, v1, s[14:15]
	global_load_ushort v83, v2, s[10:11]
	global_load_dword v84, v5, s[12:13]
	s_add_u32 s6, s6, 0x2000
	s_addc_u32 s7, s7, 0
	s_add_u32 s8, s8, 0x2000
	s_addc_u32 s9, s9, 0
	s_add_u32 s14, s14, 0x2000
	s_addc_u32 s15, s15, 0
	s_add_u32 s10, s10, 0x1000
	s_addc_u32 s11, s11, 0
	s_add_u32 s12, s12, 0x80
	s_addc_u32 s13, s13, 0
	global_load_dword v85, v1, s[6:7]
	global_load_dword v86, v1, s[8:9]
	global_load_dword v87, v1, s[14:15]
	global_load_ushort v88, v2, s[10:11]
	global_load_dword v89, v5, s[12:13]
	s_add_u32 s6, s6, 0x2000
	s_addc_u32 s7, s7, 0
	s_add_u32 s8, s8, 0x2000
	s_addc_u32 s9, s9, 0
	s_add_u32 s14, s14, 0x2000
	s_addc_u32 s15, s15, 0
	s_add_u32 s10, s10, 0x1000
	s_addc_u32 s11, s11, 0
	s_add_u32 s12, s12, 0x80
	s_addc_u32 s13, s13, 0
	global_load_dword v90, v1, s[6:7]
	global_load_dword v91, v1, s[8:9]
	global_load_dword v92, v1, s[14:15]
	global_load_ushort v93, v2, s[10:11]
	global_load_dword v94, v5, s[12:13]
	s_add_u32 s6, s6, 0x2000
	s_addc_u32 s7, s7, 0
	s_add_u32 s8, s8, 0x2000
	s_addc_u32 s9, s9, 0
	s_add_u32 s14, s14, 0x2000
	s_addc_u32 s15, s15, 0
	s_add_u32 s10, s10, 0x1000
	s_addc_u32 s11, s11, 0
	s_add_u32 s12, s12, 0x80
	s_addc_u32 s13, s13, 0
	global_load_dword v95, v1, s[6:7]
	global_load_dword v96, v1, s[8:9]
	global_load_dword v97, v1, s[14:15]
	global_load_ushort v98, v2, s[10:11]
	global_load_dword v99, v5, s[12:13]
	s_add_u32 s6, s6, 0x2000
	s_addc_u32 s7, s7, 0
	s_add_u32 s8, s8, 0x2000
	s_addc_u32 s9, s9, 0
	s_add_u32 s14, s14, 0x2000
	s_addc_u32 s15, s15, 0
	s_add_u32 s10, s10, 0x1000
	s_addc_u32 s11, s11, 0
	s_add_u32 s12, s12, 0x80
	s_addc_u32 s13, s13, 0
	global_load_dword v100, v1, s[6:7]
	global_load_dword v101, v1, s[8:9]
	global_load_dword v102, v1, s[14:15]
	global_load_ushort v103, v2, s[10:11]
	global_load_dword v104, v5, s[12:13]
	s_add_u32 s6, s6, 0x2000
	s_addc_u32 s7, s7, 0
	s_add_u32 s8, s8, 0x2000
	s_addc_u32 s9, s9, 0
	s_add_u32 s14, s14, 0x2000
	s_addc_u32 s15, s15, 0
	s_add_u32 s10, s10, 0x1000
	s_addc_u32 s11, s11, 0
	s_add_u32 s12, s12, 0x80
	s_addc_u32 s13, s13, 0
	global_load_dword v105, v1, s[6:7]
	global_load_dword v106, v1, s[8:9]
	global_load_dword v107, v1, s[14:15]
	global_load_ushort v108, v2, s[10:11]
	global_load_dword v109, v5, s[12:13]
	s_add_u32 s6, s6, 0x2000
	s_addc_u32 s7, s7, 0
	s_add_u32 s8, s8, 0x2000
	s_addc_u32 s9, s9, 0
	s_add_u32 s14, s14, 0x2000
	s_addc_u32 s15, s15, 0
	s_add_u32 s10, s10, 0x1000
	s_addc_u32 s11, s11, 0
	s_add_u32 s12, s12, 0x80
	s_addc_u32 s13, s13, 0
	global_load_dword v110, v1, s[6:7]
	global_load_dword v111, v1, s[8:9]
	global_load_dword v112, v1, s[14:15]
	global_load_ushort v113, v2, s[10:11]
	global_load_dword v114, v5, s[12:13]
	s_add_u32 s6, s6, 0x2000
	s_addc_u32 s7, s7, 0
	s_add_u32 s8, s8, 0x2000
	s_addc_u32 s9, s9, 0
	s_add_u32 s14, s14, 0x2000
	s_addc_u32 s15, s15, 0
	s_add_u32 s10, s10, 0x1000
	s_addc_u32 s11, s11, 0
	s_add_u32 s12, s12, 0x80
	s_addc_u32 s13, s13, 0
	global_load_dword v115, v1, s[6:7]
	global_load_dword v116, v1, s[8:9]
	global_load_dword v117, v1, s[14:15]
	global_load_ushort v118, v2, s[10:11]
	global_load_dword v119, v5, s[12:13]
	s_add_u32 s6, s6, 0x2000
	s_addc_u32 s7, s7, 0
	s_add_u32 s8, s8, 0x2000
	s_addc_u32 s9, s9, 0
	s_add_u32 s14, s14, 0x2000
	s_addc_u32 s15, s15, 0
	s_add_u32 s10, s10, 0x1000
	s_addc_u32 s11, s11, 0
	s_add_u32 s12, s12, 0x80
	s_addc_u32 s13, s13, 0
; #define LAS __attribute__((address_space(3)))
; __device__ __forceinline__ void rw_post(Frame& F) {
;     ...
;             if (k > 0) {
;                 LAS float* cs = (LAS float*)(F.lds + 131072 + F.wave * 1024);
; #pragma unroll
;                 for (int hf = 0; hf < 2; ++hf) {
; #pragma unroll
;                     for (int q = 0; q < 4; ++q) cs[q * 64 + lane] = cc[4 * hf + q];
;                     asm volatile("s_waitcnt lgkmcnt(0)" ::: "memory");
; #pragma unroll
;                     for (int q = 0; q < 4; ++q) { f32x4 a = (f32x4){0.f, 0.f, 0.f, 0.f};
; #pragma unroll
;                         for (int i = 0; i < 16; ++i) a = __builtin_elementwise_fma(Sr[i], *(const LAS f32x4*)(cs + q * 64 + 4 * i), a);
;                         y[4 * hf + q] += (a[0] + a[1]) + (a[2] + a[3]); }
;                     asm volatile("s_waitcnt lgkmcnt(0)" ::: "memory"); }
.Lpo_nopf:
	s_cmp_eq_u32 s23, 0
	s_cbranch_scc1 .Lpo_nc4
	ds_write_b32 v3, v142
	ds_write_b32 v3, v147 offset:256
	ds_write_b32 v3, v152 offset:512
	ds_write_b32 v3, v157 offset:768
	s_waitcnt lgkmcnt(0)
	ds_read_b128 v[204:207], v4 offset:0
	ds_read_b128 v[208:211], v4 offset:256
	ds_read_b128 v[212:215], v4 offset:512
	ds_read_b128 v[216:219], v4 offset:768
	ds_read_b128 v[220:223], v4 offset:16
	ds_read_b128 v[224:227], v4 offset:272
	ds_read_b128 v[228:231], v4 offset:528
	ds_read_b128 v[232:235], v4 offset:784
	s_waitcnt lgkmcnt(4)
	v_pk_mul_f32 v[184:185], v[16:17], v[204:205]
	v_pk_mul_f32 v[188:189], v[16:17], v[208:209]
	v_pk_mul_f32 v[192:193], v[16:17], v[212:213]
	v_pk_mul_f32 v[196:197], v[16:17], v[216:217]
	v_pk_mul_f32 v[186:187], v[18:19], v[206:207]
	v_pk_mul_f32 v[190:191], v[18:19], v[210:211]
	v_pk_mul_f32 v[194:195], v[18:19], v[214:215]
	v_pk_mul_f32 v[198:199], v[18:19], v[218:219]
	ds_read_b128 v[204:207], v4 offset:32
	ds_read_b128 v[208:211], v4 offset:288
	ds_read_b128 v[212:215], v4 offset:544
	ds_read_b128 v[216:219], v4 offset:800
	s_waitcnt lgkmcnt(4)
	v_pk_fma_f32 v[184:185], v[20:21], v[220:221], v[184:185]
	v_pk_fma_f32 v[188:189], v[20:21], v[224:225], v[188:189]
	v_pk_fma_f32 v[192:193], v[20:21], v[228:229], v[192:193]
	v_pk_fma_f32 v[196:197], v[20:21], v[232:233], v[196:197]
	v_pk_fma_f32 v[186:187], v[22:23], v[222:223], v[186:187]
	v_pk_fma_f32 v[190:191], v[22:23], v[226:227], v[190:191]
	v_pk_fma_f32 v[194:195], v[22:23], v[230:231], v[194:195]
	v_pk_fma_f32 v[198:199], v[22:23], v[234:235], v[198:199]
	ds_read_b128 v[220:223], v4 offset:48
	ds_read_b128 v[224:227], v4 offset:304
	ds_read_b128 v[228:231], v4 offset:560
	ds_read_b128 v[232:235], v4 offset:816
	s_waitcnt lgkmcnt(4)
	v_pk_fma_f32 v[184:185], v[24:25], v[204:205], v[184:185]
	v_pk_fma_f32 v[188:189], v[24:25], v[208:209], v[188:189]
	v_pk_fma_f32 v[192:193], v[24:25], v[212:213], v[192:193]
	v_pk_fma_f32 v[196:197], v[24:25], v[216:217], v[196:197]
	v_pk_fma_f32 v[186:187], v[26:27], v[206:207], v[186:187]
	v_pk_fma_f32 v[190:191], v[26:27], v[210:211], v[190:191]
	v_pk_fma_f32 v[194:195], v[26:27], v[214:215], v[194:195]
	v_pk_fma_f32 v[198:199], v[26:27], v[218:219], v[198:199]
	ds_read_b128 v[204:207], v4 offset:64
	ds_read_b128 v[208:211], v4 offset:320
	ds_read_b128 v[212:215], v4 offset:576
	ds_read_b128 v[216:219], v4 offset:832
	s_waitcnt lgkmcnt(4)
	v_pk_fma_f32 v[184:185], v[28:29], v[220:221], v[184:185]
	v_pk_fma_f32 v[188:189], v[28:29], v[224:225], v[188:189]
	v_pk_fma_f32 v[192:193], v[28:29], v[228:229], v[192:193]
	v_pk_fma_f32 v[196:197], v[28:29], v[232:233], v[196:197]
	v_pk_fma_f32 v[186:187], v[30:31], v[222:223], v[186:187]
	v_pk_fma_f32 v[190:191], v[30:31], v[226:227], v[190:191]
	v_pk_fma_f32 v[194:195], v[30:31], v[230:231], v[194:195]
	v_pk_fma_f32 v[198:199], v[30:31], v[234:235], v[198:199]
	ds_read_b128 v[220:223], v4 offset:80
	ds_read_b128 v[224:227], v4 offset:336
	ds_read_b128 v[228:231], v4 offset:592
	ds_read_b128 v[232:235], v4 offset:848
	s_waitcnt lgkmcnt(4)
	v_pk_fma_f32 v[184:185], v[32:33], v[204:205], v[184:185]
	v_pk_fma_f32 v[188:189], v[32:33], v[208:209], v[188:189]
	v_pk_fma_f32 v[192:193], v[32:33], v[212:213], v[192:193]
	v_pk_fma_f32 v[196:197], v[32:33], v[216:217], v[196:197]
	v_pk_fma_f32 v[186:187], v[34:35], v[206:207], v[186:187]
	v_pk_fma_f32 v[190:191], v[34:35], v[210:211], v[190:191]
	v_pk_fma_f32 v[194:195], v[34:35], v[214:215], v[194:195]
	v_pk_fma_f32 v[198:199], v[34:35], v[218:219], v[198:199]
	ds_read_b128 v[204:207], v4 offset:96
	ds_read_b128 v[208:211], v4 offset:352
	ds_read_b128 v[212:215], v4 offset:608
	ds_read_b128 v[216:219], v4 offset:864
	s_waitcnt lgkmcnt(4)
	v_pk_fma_f32 v[184:185], v[36:37], v[220:221], v[184:185]
	v_pk_fma_f32 v[188:189], v[36:37], v[224:225], v[188:189]
	v_pk_fma_f32 v[192:193], v[36:37], v[228:229], v[192:193]
	v_pk_fma_f32 v[196:197], v[36:37], v[232:233], v[196:197]
	v_pk_fma_f32 v[186:187], v[38:39], v[222:223], v[186:187]
	v_pk_fma_f32 v[190:191], v[38:39], v[226:227], v[190:191]
	v_pk_fma_f32 v[194:195], v[38:39], v[230:231], v[194:195]
	v_pk_fma_f32 v[198:199], v[38:39], v[234:235], v[198:199]
	ds_read_b128 v[220:223], v4 offset:112
	ds_read_b128 v[224:227], v4 offset:368
	ds_read_b128 v[228:231], v4 offset:624
	ds_read_b128 v[232:235], v4 offset:880
	s_waitcnt lgkmcnt(4)
	v_pk_fma_f32 v[184:185], v[40:41], v[204:205], v[184:185]
	v_pk_fma_f32 v[188:189], v[40:41], v[208:209], v[188:189]
	v_pk_fma_f32 v[192:193], v[40:41], v[212:213], v[192:193]
	v_pk_fma_f32 v[196:197], v[40:41], v[216:217], v[196:197]
	v_pk_fma_f32 v[186:187], v[42:43], v[206:207], v[186:187]
	v_pk_fma_f32 v[190:191], v[42:43], v[210:211], v[190:191]
	v_pk_fma_f32 v[194:195], v[42:43], v[214:215], v[194:195]
	v_pk_fma_f32 v[198:199], v[42:43], v[218:219], v[198:199]
	ds_read_b128 v[204:207], v4 offset:128
	ds_read_b128 v[208:211], v4 offset:384
	ds_read_b128 v[212:215], v4 offset:640
	ds_read_b128 v[216:219], v4 offset:896
	s_waitcnt lgkmcnt(4)
	v_pk_fma_f32 v[184:185], v[44:45], v[220:221], v[184:185]
	v_pk_fma_f32 v[188:189], v[44:45], v[224:225], v[188:189]
	v_pk_fma_f32 v[192:193], v[44:45], v[228:229], v[192:193]
	v_pk_fma_f32 v[196:197], v[44:45], v[232:233], v[196:197]
	v_pk_fma_f32 v[186:187], v[46:47], v[222:223], v[186:187]
	v_pk_fma_f32 v[190:191], v[46:47], v[226:227], v[190:191]
	v_pk_fma_f32 v[194:195], v[46:47], v[230:231], v[194:195]
	v_pk_fma_f32 v[198:199], v[46:47], v[234:235], v[198:199]
	ds_read_b128 v[220:223], v4 offset:144
	ds_read_b128 v[224:227], v4 offset:400
	ds_read_b128 v[228:231], v4 offset:656
	ds_read_b128 v[232:235], v4 offset:912
	s_waitcnt lgkmcnt(4)
; #define LAS __attribute__((address_space(3)))
; __device__ __forceinline__ void rw_post(Frame& F) {
;     ...
;                 for (int hf = 0; hf < 2; ++hf) {
; #pragma unroll
;                     for (int q = 0; q < 4; ++q) cs[q * 64 + lane] = cc[4 * hf + q];
;                     asm volatile("s_waitcnt lgkmcnt(0)" ::: "memory");
; #pragma unroll
;                     for (int q = 0; q < 4; ++q) { f32x4 a = (f32x4){0.f, 0.f, 0.f, 0.f};
; #pragma unroll
;                         for (int i = 0; i < 16; ++i) a = __builtin_elementwise_fma(Sr[i], *(const LAS f32x4*)(cs + q * 64 + 4 * i), a);
;                         y[4 * hf + q] += (a[0] + a[1]) + (a[2] + a[3]); }
;                     asm volatile("s_waitcnt lgkmcnt(0)" ::: "memory"); }
	v_pk_fma_f32 v[184:185], v[48:49], v[204:205], v[184:185]
	v_pk_fma_f32 v[188:189], v[48:49], v[208:209], v[188:189]
	v_pk_fma_f32 v[192:193], v[48:49], v[212:213], v[192:193]
	v_pk_fma_f32 v[196:197], v[48:49], v[216:217], v[196:197]
	v_pk_fma_f32 v[186:187], v[50:51], v[206:207], v[186:187]
	v_pk_fma_f32 v[190:191], v[50:51], v[210:211], v[190:191]
	v_pk_fma_f32 v[194:195], v[50:51], v[214:215], v[194:195]
	v_pk_fma_f32 v[198:199], v[50:51], v[218:219], v[198:199]
	ds_read_b128 v[204:207], v4 offset:160
	ds_read_b128 v[208:211], v4 offset:416
	ds_read_b128 v[212:215], v4 offset:672
	ds_read_b128 v[216:219], v4 offset:928
	s_waitcnt lgkmcnt(4)
	v_pk_fma_f32 v[184:185], v[52:53], v[220:221], v[184:185]
	v_pk_fma_f32 v[188:189], v[52:53], v[224:225], v[188:189]
	v_pk_fma_f32 v[192:193], v[52:53], v[228:229], v[192:193]
	v_pk_fma_f32 v[196:197], v[52:53], v[232:233], v[196:197]
	v_pk_fma_f32 v[186:187], v[54:55], v[222:223], v[186:187]
	v_pk_fma_f32 v[190:191], v[54:55], v[226:227], v[190:191]
	v_pk_fma_f32 v[194:195], v[54:55], v[230:231], v[194:195]
	v_pk_fma_f32 v[198:199], v[54:55], v[234:235], v[198:199]
	ds_read_b128 v[220:223], v4 offset:176
	ds_read_b128 v[224:227], v4 offset:432
	ds_read_b128 v[228:231], v4 offset:688
	ds_read_b128 v[232:235], v4 offset:944
	s_waitcnt lgkmcnt(4)
	v_pk_fma_f32 v[184:185], v[56:57], v[204:205], v[184:185]
	v_pk_fma_f32 v[188:189], v[56:57], v[208:209], v[188:189]
	v_pk_fma_f32 v[192:193], v[56:57], v[212:213], v[192:193]
	v_pk_fma_f32 v[196:197], v[56:57], v[216:217], v[196:197]
	v_pk_fma_f32 v[186:187], v[58:59], v[206:207], v[186:187]
	v_pk_fma_f32 v[190:191], v[58:59], v[210:211], v[190:191]
	v_pk_fma_f32 v[194:195], v[58:59], v[214:215], v[194:195]
	v_pk_fma_f32 v[198:199], v[58:59], v[218:219], v[198:199]
	ds_read_b128 v[204:207], v4 offset:192
	ds_read_b128 v[208:211], v4 offset:448
	ds_read_b128 v[212:215], v4 offset:704
	ds_read_b128 v[216:219], v4 offset:960
	s_waitcnt lgkmcnt(4)
	v_pk_fma_f32 v[184:185], v[60:61], v[220:221], v[184:185]
	v_pk_fma_f32 v[188:189], v[60:61], v[224:225], v[188:189]
	v_pk_fma_f32 v[192:193], v[60:61], v[228:229], v[192:193]
	v_pk_fma_f32 v[196:197], v[60:61], v[232:233], v[196:197]
	v_pk_fma_f32 v[186:187], v[62:63], v[222:223], v[186:187]
	v_pk_fma_f32 v[190:191], v[62:63], v[226:227], v[190:191]
	v_pk_fma_f32 v[194:195], v[62:63], v[230:231], v[194:195]
	v_pk_fma_f32 v[198:199], v[62:63], v[234:235], v[198:199]
	ds_read_b128 v[220:223], v4 offset:208
	ds_read_b128 v[224:227], v4 offset:464
	ds_read_b128 v[228:231], v4 offset:720
	ds_read_b128 v[232:235], v4 offset:976
	s_waitcnt lgkmcnt(4)
	v_pk_fma_f32 v[184:185], v[64:65], v[204:205], v[184:185]
	v_pk_fma_f32 v[188:189], v[64:65], v[208:209], v[188:189]
	v_pk_fma_f32 v[192:193], v[64:65], v[212:213], v[192:193]
	v_pk_fma_f32 v[196:197], v[64:65], v[216:217], v[196:197]
	v_pk_fma_f32 v[186:187], v[66:67], v[206:207], v[186:187]
	v_pk_fma_f32 v[190:191], v[66:67], v[210:211], v[190:191]
	v_pk_fma_f32 v[194:195], v[66:67], v[214:215], v[194:195]
	v_pk_fma_f32 v[198:199], v[66:67], v[218:219], v[198:199]
	ds_read_b128 v[204:207], v4 offset:224
	ds_read_b128 v[208:211], v4 offset:480
	ds_read_b128 v[212:215], v4 offset:736
	ds_read_b128 v[216:219], v4 offset:992
	s_waitcnt lgkmcnt(4)
	v_pk_fma_f32 v[184:185], v[68:69], v[220:221], v[184:185]
	v_pk_fma_f32 v[188:189], v[68:69], v[224:225], v[188:189]
	v_pk_fma_f32 v[192:193], v[68:69], v[228:229], v[192:193]
	v_pk_fma_f32 v[196:197], v[68:69], v[232:233], v[196:197]
	v_pk_fma_f32 v[186:187], v[70:71], v[222:223], v[186:187]
	v_pk_fma_f32 v[190:191], v[70:71], v[226:227], v[190:191]
	v_pk_fma_f32 v[194:195], v[70:71], v[230:231], v[194:195]
	v_pk_fma_f32 v[198:199], v[70:71], v[234:235], v[198:199]
	ds_read_b128 v[220:223], v4 offset:240
	ds_read_b128 v[224:227], v4 offset:496
	ds_read_b128 v[228:231], v4 offset:752
	ds_read_b128 v[232:235], v4 offset:1008
	s_waitcnt lgkmcnt(4)
	v_pk_fma_f32 v[184:185], v[72:73], v[204:205], v[184:185]
	v_pk_fma_f32 v[188:189], v[72:73], v[208:209], v[188:189]
	v_pk_fma_f32 v[192:193], v[72:73], v[212:213], v[192:193]
	v_pk_fma_f32 v[196:197], v[72:73], v[216:217], v[196:197]
	v_pk_fma_f32 v[186:187], v[74:75], v[206:207], v[186:187]
	v_pk_fma_f32 v[190:191], v[74:75], v[210:211], v[190:191]
	v_pk_fma_f32 v[194:195], v[74:75], v[214:215], v[194:195]
	v_pk_fma_f32 v[198:199], v[74:75], v[218:219], v[198:199]
	s_waitcnt lgkmcnt(0)
	v_pk_fma_f32 v[184:185], v[76:77], v[220:221], v[184:185]
	v_pk_fma_f32 v[188:189], v[76:77], v[224:225], v[188:189]
	v_pk_fma_f32 v[192:193], v[76:77], v[228:229], v[192:193]
	v_pk_fma_f32 v[196:197], v[76:77], v[232:233], v[196:197]
	v_pk_fma_f32 v[186:187], v[78:79], v[222:223], v[186:187]
	v_pk_fma_f32 v[190:191], v[78:79], v[226:227], v[190:191]
	v_pk_fma_f32 v[194:195], v[78:79], v[230:231], v[194:195]
	v_pk_fma_f32 v[198:199], v[78:79], v[234:235], v[198:199]
	v_add_f32_e32 v184, v184, v185
	v_add_f32_e32 v188, v188, v189
	v_add_f32_e32 v192, v192, v193
	v_add_f32_e32 v196, v196, v197
	v_add_f32_e32 v186, v186, v187
	v_add_f32_e32 v190, v190, v191
	v_add_f32_e32 v194, v194, v195
	v_add_f32_e32 v198, v198, v199
	v_add_f32_e32 v184, v184, v186
	v_add_f32_e32 v188, v188, v190
	v_add_f32_e32 v192, v192, v194
	v_add_f32_e32 v196, v196, v198
	v_add_f32_e32 v140, v140, v184
	v_add_f32_e32 v145, v145, v188
	v_add_f32_e32 v150, v150, v192
	v_add_f32_e32 v155, v155, v196
; __device__ __forceinline__ float dpp_xor1(float x) { return __builtin_bit_cast(float, __builtin_amdgcn_update_dpp(0, __builtin_bit_cast(int, x), 0xB1, 0xF, 0xF, true)); }
; __device__ __forceinline__ float dpp_xor2(float x) { return __builtin_bit_cast(float, __builtin_amdgcn_update_dpp(0, __builtin_bit_cast(int, x), 0x4E, 0xF, 0xF, true)); }
; __device__ __forceinline__ float dpp_hmir(float x) { return __builtin_bit_cast(float, __builtin_amdgcn_update_dpp(0, __builtin_bit_cast(int, x), 0x141, 0xF, 0xF, true)); }
; __device__ __forceinline__ float dpp_mir(float x)  { return __builtin_bit_cast(float, __builtin_amdgcn_update_dpp(0, __builtin_bit_cast(int, x), 0x140, 0xF, 0xF, true)); }
; __device__ __forceinline__ float red16(float x) { x += dpp_xor1(x); x += dpp_xor2(x); x += dpp_hmir(x); x += dpp_mir(x); return x; }
; __device__ __forceinline__ float wsum(float x) {
;     x = red16(x); const int xi = __builtin_bit_cast(int, x);
;     const float r0 = __builtin_bit_cast(float, __builtin_amdgcn_readlane(xi, 0)), r1 = __builtin_bit_cast(float, __builtin_amdgcn_readlane(xi, 16));
;     const float r2 = __builtin_bit_cast(float, __builtin_amdgcn_readlane(xi, 32)), r3 = __builtin_bit_cast(float, __builtin_amdgcn_readlane(xi, 48));
;     return (r0 + r1) + (r2 + r3);
; }
; __device__ __forceinline__ void rw_post(Frame& F) {
;     ...
;                 const float mean = wsum(y[q]) * (1.f / 64.f); const float dv = y[q] - mean; const float var = wsum(dv * dv) * (1.f / 64.f);
;                 const float yn = dv * (1.f / sqrtf(var + 64e-5f)) * g_ + b_;
.Lpo_nc4:
	v_add_f32_dpp v168, v140, v140 quad_perm:[1,0,3,2] row_mask:0xf bank_mask:0xf bound_ctrl:1
	v_add_f32_dpp v174, v145, v145 quad_perm:[1,0,3,2] row_mask:0xf bank_mask:0xf bound_ctrl:1
	v_add_f32_dpp v241, v150, v150 quad_perm:[1,0,3,2] row_mask:0xf bank_mask:0xf bound_ctrl:1
	v_add_f32_dpp v247, v155, v155 quad_perm:[1,0,3,2] row_mask:0xf bank_mask:0xf bound_ctrl:1
	v_add_f32_dpp v168, v168, v168 quad_perm:[2,3,0,1] row_mask:0xf bank_mask:0xf bound_ctrl:1
	v_add_f32_dpp v174, v174, v174 quad_perm:[2,3,0,1] row_mask:0xf bank_mask:0xf bound_ctrl:1
	v_add_f32_dpp v241, v241, v241 quad_perm:[2,3,0,1] row_mask:0xf bank_mask:0xf bound_ctrl:1
	v_add_f32_dpp v247, v247, v247 quad_perm:[2,3,0,1] row_mask:0xf bank_mask:0xf bound_ctrl:1
	v_add_f32_dpp v168, v168, v168 row_half_mirror row_mask:0xf bank_mask:0xf bound_ctrl:1
	v_add_f32_dpp v174, v174, v174 row_half_mirror row_mask:0xf bank_mask:0xf bound_ctrl:1
	v_add_f32_dpp v241, v241, v241 row_half_mirror row_mask:0xf bank_mask:0xf bound_ctrl:1
	v_add_f32_dpp v247, v247, v247 row_half_mirror row_mask:0xf bank_mask:0xf bound_ctrl:1
	v_add_f32_dpp v168, v168, v168 row_mirror row_mask:0xf bank_mask:0xf bound_ctrl:1
	v_add_f32_dpp v174, v174, v174 row_mirror row_mask:0xf bank_mask:0xf bound_ctrl:1
	v_add_f32_dpp v241, v241, v241 row_mirror row_mask:0xf bank_mask:0xf bound_ctrl:1
	v_add_f32_dpp v247, v247, v247 row_mirror row_mask:0xf bank_mask:0xf bound_ctrl:1
	v_readlane_b32 s36, v168, 16
	v_readlane_b32 s40, v174, 16
	v_readlane_b32 s44, v241, 16
	v_readlane_b32 s48, v247, 16
	v_readlane_b32 s37, v168, 48
	v_readlane_b32 s41, v174, 48
	v_readlane_b32 s45, v241, 48
	v_readlane_b32 s49, v247, 48
	v_readlane_b32 s38, v168, 0
	v_readlane_b32 s42, v174, 0
	v_readlane_b32 s46, v241, 0
	v_readlane_b32 s50, v247, 0
	v_readlane_b32 s39, v168, 32
	v_readlane_b32 s43, v174, 32
	v_readlane_b32 s47, v241, 32
	v_readlane_b32 s51, v247, 32
	v_mov_b32_e32 v168, s36
	v_mov_b32_e32 v174, s40
	v_mov_b32_e32 v241, s44
	v_mov_b32_e32 v247, s48
	v_mov_b32_e32 v169, s37
	v_mov_b32_e32 v175, s41
	v_mov_b32_e32 v242, s45
	v_mov_b32_e32 v248, s49
	v_add_f32_e32 v168, s38, v168
	v_add_f32_e32 v174, s42, v174
	v_add_f32_e32 v241, s46, v241
	v_add_f32_e32 v247, s50, v247
	v_add_f32_e32 v169, s39, v169
	v_add_f32_e32 v175, s43, v175
	v_add_f32_e32 v242, s47, v242
	v_add_f32_e32 v248, s51, v248
	v_add_f32_e32 v168, v168, v169
	v_add_f32_e32 v174, v174, v175
	v_add_f32_e32 v241, v241, v242
	v_add_f32_e32 v247, v247, v248
	v_fmamk_f32 v140, v168, 0xbc800000, v140
	v_fmamk_f32 v145, v174, 0xbc800000, v145
	v_fmamk_f32 v150, v241, 0xbc800000, v150
	v_fmamk_f32 v155, v247, 0xbc800000, v155
	v_mul_f32_e32 v168, v140, v140
	v_mul_f32_e32 v174, v145, v145
	v_mul_f32_e32 v241, v150, v150
	v_mul_f32_e32 v247, v155, v155
	v_mov_b32_dpp v168, v168 quad_perm:[1,0,3,2] row_mask:0xf bank_mask:0xf bound_ctrl:1
	v_mov_b32_dpp v174, v174 quad_perm:[1,0,3,2] row_mask:0xf bank_mask:0xf bound_ctrl:1
	v_mov_b32_dpp v241, v241 quad_perm:[1,0,3,2] row_mask:0xf bank_mask:0xf bound_ctrl:1
	v_mov_b32_dpp v247, v247 quad_perm:[1,0,3,2] row_mask:0xf bank_mask:0xf bound_ctrl:1
	v_fmac_f32_e32 v168, v140, v140
	v_fmac_f32_e32 v174, v145, v145
	v_fmac_f32_e32 v241, v150, v150
	v_fmac_f32_e32 v247, v155, v155
	v_add_f32_dpp v168, v168, v168 quad_perm:[2,3,0,1] row_mask:0xf bank_mask:0xf bound_ctrl:1
	v_add_f32_dpp v174, v174, v174 quad_perm:[2,3,0,1] row_mask:0xf bank_mask:0xf bound_ctrl:1
	v_add_f32_dpp v241, v241, v241 quad_perm:[2,3,0,1] row_mask:0xf bank_mask:0xf bound_ctrl:1
	v_add_f32_dpp v247, v247, v247 quad_perm:[2,3,0,1] row_mask:0xf bank_mask:0xf bound_ctrl:1
	v_add_f32_dpp v168, v168, v168 row_half_mirror row_mask:0xf bank_mask:0xf bound_ctrl:1
	v_add_f32_dpp v174, v174, v174 row_half_mirror row_mask:0xf bank_mask:0xf bound_ctrl:1
	v_add_f32_dpp v241, v241, v241 row_half_mirror row_mask:0xf bank_mask:0xf bound_ctrl:1
	v_add_f32_dpp v247, v247, v247 row_half_mirror row_mask:0xf bank_mask:0xf bound_ctrl:1
	v_add_f32_dpp v168, v168, v168 row_mirror row_mask:0xf bank_mask:0xf bound_ctrl:1
	v_add_f32_dpp v174, v174, v174 row_mirror row_mask:0xf bank_mask:0xf bound_ctrl:1
	v_add_f32_dpp v241, v241, v241 row_mirror row_mask:0xf bank_mask:0xf bound_ctrl:1
	v_add_f32_dpp v247, v247, v247 row_mirror row_mask:0xf bank_mask:0xf bound_ctrl:1
	v_readlane_b32 s36, v168, 16
	v_readlane_b32 s40, v174, 16
	v_readlane_b32 s44, v241, 16
	v_readlane_b32 s48, v247, 16
	v_readlane_b32 s37, v168, 48
	v_readlane_b32 s41, v174, 48
	v_readlane_b32 s45, v241, 48
	v_readlane_b32 s49, v247, 48
	v_readlane_b32 s38, v168, 0
	v_readlane_b32 s42, v174, 0
	v_readlane_b32 s46, v241, 0
	v_readlane_b32 s50, v247, 0
	v_readlane_b32 s39, v168, 32
	v_readlane_b32 s43, v174, 32
	v_readlane_b32 s47, v241, 32
	v_readlane_b32 s51, v247, 32
	v_mov_b32_e32 v168, s36
	v_mov_b32_e32 v174, s40
	v_mov_b32_e32 v241, s44
	v_mov_b32_e32 v247, s48
	v_mov_b32_e32 v169, s37
	v_mov_b32_e32 v175, s41
	v_mov_b32_e32 v242, s45
	v_mov_b32_e32 v248, s49
	v_add_f32_e32 v168, s38, v168
	v_add_f32_e32 v174, s42, v174
	v_add_f32_e32 v241, s46, v241
	v_add_f32_e32 v247, s50, v247
	v_add_f32_e32 v169, s39, v169
	v_add_f32_e32 v175, s43, v175
	v_add_f32_e32 v242, s47, v242
	v_add_f32_e32 v248, s51, v248
	v_add_f32_e32 v168, v168, v169
	v_add_f32_e32 v174, v174, v175
	v_add_f32_e32 v241, v241, v242
	v_add_f32_e32 v247, v247, v248
	v_fmamk_f32 v168, v168, 0x3c800000, v9
	v_fmamk_f32 v174, v174, 0x3c800000, v9
	v_fmamk_f32 v241, v241, 0x3c800000, v9
	v_fmamk_f32 v247, v247, 0x3c800000, v9
; __device__ __forceinline__ float bf2f(bf16 x) { return __uint_as_float(((unsigned)x) << 16); }
; __device__ __forceinline__ unsigned f2bf(float f) { return cvt_pk_bf16(f, 0.f) & 0xffffu; }
; __device__ __forceinline__ void rw_post(Frame& F) {
;     ...
;                 const float mean = wsum(y[q]) * (1.f / 64.f); const float dv = y[q] - mean; const float var = wsum(dv * dv) * (1.f / 64.f);
;                 const float yn = dv * (1.f / sqrtf(var + 64e-5f)) * g_ + b_;
;                 OB[(size_t)row * DH + col] = (bf16)f2bf((yn + rk[q] * vv[q]) * bf2f(gg[q])); }
; #pragma unroll
;             for (int q = 0; q < 8; ++q) { y[q] = ny[q]; vv[q] = nv[q]; gg[q] = ng[q]; rk[q] = nr[q]; cc[q] = nc[q]; }
;         }
;     ...
;     }
	v_mul_f32_e32 v169, 0x4f800000, v168
	v_mul_f32_e32 v175, 0x4f800000, v174
	v_mul_f32_e32 v242, 0x4f800000, v241
	v_mul_f32_e32 v248, 0x4f800000, v247
	v_cmp_gt_f32_e64 s[52:53], s68, v168
	v_cmp_gt_f32_e64 s[54:55], s68, v174
	v_cmp_gt_f32_e64 s[56:57], s68, v241
	v_cmp_gt_f32_e64 s[58:59], s68, v247
	v_mov_b32_e32 v170, v168
	v_mov_b32_e32 v176, v174
	v_mov_b32_e32 v243, v241
	v_mov_b32_e32 v249, v247
	v_cndmask_b32_e64 v168, v170, v169, s[52:53]
	v_cndmask_b32_e64 v174, v176, v175, s[54:55]
	v_cndmask_b32_e64 v241, v243, v242, s[56:57]
	v_cndmask_b32_e64 v247, v249, v248, s[58:59]
	v_sqrt_f32_e32 v169, v168
	v_sqrt_f32_e32 v175, v174
	v_sqrt_f32_e32 v242, v241
	v_sqrt_f32_e32 v248, v247
	v_add_u32_e32 v170, -1, v169
	v_add_u32_e32 v176, -1, v175
	v_add_u32_e32 v243, -1, v242
	v_add_u32_e32 v249, -1, v248
	v_fma_f32 v171, -v170, v169, v168
	v_fma_f32 v177, -v176, v175, v174
	v_fma_f32 v244, -v243, v242, v241
	v_fma_f32 v250, -v249, v248, v247
	v_cmp_ge_f32_e64 s[60:61], 0, v171
	v_cmp_ge_f32_e64 s[62:63], 0, v177
	v_cmp_ge_f32_e64 s[64:65], 0, v244
	v_cmp_ge_f32_e64 s[66:67], 0, v250
	v_add_u32_e32 v171, 1, v169
	v_add_u32_e32 v177, 1, v175
	v_add_u32_e32 v244, 1, v242
	v_add_u32_e32 v250, 1, v248
	v_cndmask_b32_e64 v170, v169, v170, s[60:61]
	v_cndmask_b32_e64 v176, v175, v176, s[62:63]
	v_cndmask_b32_e64 v243, v242, v243, s[64:65]
	v_cndmask_b32_e64 v249, v248, v249, s[66:67]
	v_fma_f32 v169, -v171, v169, v168
	v_fma_f32 v175, -v177, v175, v174
	v_fma_f32 v242, -v244, v242, v241
	v_fma_f32 v248, -v250, v248, v247
	v_cmp_lt_f32_e64 s[60:61], 0, v169
	v_cmp_lt_f32_e64 s[62:63], 0, v175
	v_cmp_lt_f32_e64 s[64:65], 0, v242
	v_cmp_lt_f32_e64 s[66:67], 0, v248
	v_cndmask_b32_e64 v169, v170, v171, s[60:61]
	v_cndmask_b32_e64 v175, v176, v177, s[62:63]
	v_cndmask_b32_e64 v242, v243, v244, s[64:65]
	v_cndmask_b32_e64 v248, v249, v250, s[66:67]
	v_mul_f32_e32 v170, 0x37800000, v169
	v_mul_f32_e32 v176, 0x37800000, v175
	v_mul_f32_e32 v243, 0x37800000, v242
	v_mul_f32_e32 v249, 0x37800000, v248
	v_cndmask_b32_e64 v169, v169, v170, s[52:53]
	v_cndmask_b32_e64 v175, v175, v176, s[54:55]
	v_cndmask_b32_e64 v242, v242, v243, s[56:57]
	v_cndmask_b32_e64 v248, v248, v249, s[58:59]
	v_cmp_class_f32_e64 s[60:61], v168, v8
	v_cmp_class_f32_e64 s[62:63], v174, v8
	v_cmp_class_f32_e64 s[64:65], v241, v8
	v_cmp_class_f32_e64 s[66:67], v247, v8
	v_cndmask_b32_e64 v168, v169, v168, s[60:61]
	v_cndmask_b32_e64 v174, v175, v174, s[62:63]
	v_cndmask_b32_e64 v241, v242, v241, s[64:65]
	v_cndmask_b32_e64 v247, v248, v247, s[66:67]
	v_div_scale_f32 v169, s[60:61], v168, v168, 1.0
	v_rcp_f32_e32 v170, v169
	s_nop 0
	v_fma_f32 v171, -v169, v170, 1.0
	v_fmac_f32_e32 v170, v171, v170
	v_div_scale_f32 v171, vcc, 1.0, v168, 1.0
	v_mul_f32_e32 v172, v171, v170
	v_fma_f32 v173, -v169, v172, v171
	v_fmac_f32_e32 v172, v173, v170
	v_fma_f32 v169, -v169, v172, v171
	v_div_fmas_f32 v169, v169, v170, v172
	v_div_fixup_f32 v168, v169, v168, 1.0
	v_div_scale_f32 v175, s[62:63], v174, v174, 1.0
	v_rcp_f32_e32 v176, v175
	s_nop 0
	v_fma_f32 v177, -v175, v176, 1.0
	v_fmac_f32_e32 v176, v177, v176
	v_div_scale_f32 v177, vcc, 1.0, v174, 1.0
	v_mul_f32_e32 v236, v177, v176
	v_fma_f32 v237, -v175, v236, v177
	v_fmac_f32_e32 v236, v237, v176
	v_fma_f32 v175, -v175, v236, v177
	v_div_fmas_f32 v175, v175, v176, v236
	v_div_fixup_f32 v174, v175, v174, 1.0
	v_div_scale_f32 v242, s[64:65], v241, v241, 1.0
	v_rcp_f32_e32 v243, v242
	s_nop 0
	v_fma_f32 v244, -v242, v243, 1.0
	v_fmac_f32_e32 v243, v244, v243
	v_div_scale_f32 v244, vcc, 1.0, v241, 1.0
	v_mul_f32_e32 v245, v244, v243
	v_fma_f32 v246, -v242, v245, v244
	v_fmac_f32_e32 v245, v246, v243
	v_fma_f32 v242, -v242, v245, v244
	v_div_fmas_f32 v242, v242, v243, v245
	v_div_fixup_f32 v241, v242, v241, 1.0
	v_div_scale_f32 v248, s[66:67], v247, v247, 1.0
	v_rcp_f32_e32 v249, v248
	s_nop 0
	v_fma_f32 v250, -v248, v249, 1.0
	v_fmac_f32_e32 v249, v250, v249
	v_div_scale_f32 v250, vcc, 1.0, v247, 1.0
	v_mul_f32_e32 v251, v250, v249
	v_fma_f32 v252, -v248, v251, v250
	v_fmac_f32_e32 v251, v252, v249
	v_fma_f32 v248, -v248, v251, v250
	v_div_fmas_f32 v248, v248, v249, v251
	v_div_fixup_f32 v247, v248, v247, 1.0
	v_mul_f32_e32 v140, v140, v168
	v_mul_f32_e32 v145, v145, v174
	v_mul_f32_e32 v150, v150, v241
	v_mul_f32_e32 v155, v155, v247
	v_lshlrev_b32_e32 v143, 16, v143
	v_lshlrev_b32_e32 v148, 16, v148
	v_lshlrev_b32_e32 v153, 16, v153
	v_lshlrev_b32_e32 v158, 16, v158
	v_fma_f32 v140, v6, v140, v7
	v_fma_f32 v145, v6, v145, v7
	v_fma_f32 v150, v6, v150, v7
	v_fma_f32 v155, v6, v155, v7
	v_fmac_f32_e32 v140, v144, v141
	v_fmac_f32_e32 v145, v149, v146
	v_fmac_f32_e32 v150, v154, v151
	v_fmac_f32_e32 v155, v159, v156
	v_mul_f32_e32 v140, v140, v143
	v_mul_f32_e32 v145, v145, v148
	v_mul_f32_e32 v150, v150, v153
	v_mul_f32_e32 v155, v155, v158
	v_cvt_pk_bf16_f32 v169, v140, v140
	v_cvt_pk_bf16_f32 v175, v145, v145
	v_cvt_pk_bf16_f32 v242, v150, v150
	v_cvt_pk_bf16_f32 v248, v155, v155
	global_store_short v2, v169, s[28:29]
	s_add_u32 s28, s28, 0x1000
	s_addc_u32 s29, s29, 0
	global_store_short v2, v175, s[28:29]
	s_add_u32 s28, s28, 0x1000
	s_addc_u32 s29, s29, 0
	global_store_short v2, v242, s[28:29]
	s_add_u32 s28, s28, 0x1000
	s_addc_u32 s29, s29, 0
	global_store_short v2, v248, s[28:29]
	s_add_u32 s28, s28, 0x1000
	s_addc_u32 s29, s29, 0
	s_waitcnt vmcnt(4)
	s_sub_u32 s25, s25, 1
	s_cmp_lg_u32 s25, 0
	s_cbranch_scc1 .Lpo_pair
	s_add_i32 s20, s20, s92
	s_cmpk_lt_i32 s20, 0x2040
	s_cbranch_scc1 .Lpo_unit
